# grid barrier: released workgroups and non-last leaders poll the cross-XCD arrival counter against (round+1)*nx; relay atomic dropped; on top of v109
# speedup vs baseline: 1.0047x; 1.0009x over previous
; __device__ __forceinline__ unsigned xb_ld(unsigned* p)              { return __hip_atomic_load(p, __ATOMIC_RELAXED, __HIP_MEMORY_SCOPE_AGENT); }
; __device__ __forceinline__ unsigned xb_add(unsigned* p, unsigned v) { return __hip_atomic_fetch_add(p, v, __ATOMIC_RELAXED, __HIP_MEMORY_SCOPE_AGENT); }
; #define XB_SPIN(cond, bar) do { unsigned _sp = 0; while (cond) { __builtin_amdgcn_s_sleep(1); \
;     if ((++_sp & 255u) == 0u) { if (xb_ld(&(bar)[XB_TMO])) break; if (_sp > XB_SPIN_CAP) { atomicAdd(&(bar)[XB_TMO], 1u); break; } } } } while (0)
; __device__ __forceinline__ void xcd_barrier(const XcdBarrier& b) {
;     ...
;         const unsigned old = xb_add(&bar[XB_XSUB(b.x)], 1u);
;         const unsigned gen = old / nloc;
;         if (old + 1u == (gen + 1u) * nloc) {
;             __builtin_amdgcn_fence(__ATOMIC_RELEASE, "agent");
;             asm volatile("s_waitcnt vmcnt(0)" ::: "memory");
;             const unsigned og = xb_add(&bar[XB_TOP], 1u);
;             const unsigned tg = og / nx;
;             if (og + 1u == (tg + 1u) * nx) xb_add(&bar[XB_TOPGEN], 1u);
;             else XB_SPIN(xb_ld(&bar[XB_TOPGEN]) == tg, bar);
;             __builtin_amdgcn_fence(__ATOMIC_ACQUIRE, "agent");
;             xb_add(&bar[XB_XGEN(b.x)], 1u);
;             asm volatile("s_waitcnt vmcnt(0)" ::: "memory");
;         } else {
;             XB_SPIN(xb_ld(&bar[XB_XGEN(b.x)]) == gen, bar);
.LBB0_139:
	s_or_b64 exec, exec, s[24:25]
	v_cvt_f32_u32_e32 v5, v3
	s_waitcnt vmcnt(0)
	v_readfirstlane_b32 s3, v4
	v_sub_u32_e32 v4, 0, v3
	v_rcp_iflag_f32_e32 v5, v5
	v_add_u32_e32 v6, s3, v2
	v_mul_f32_e32 v5, 0x4f7ffffe, v5
	v_cvt_u32_f32_e32 v5, v5
	v_mul_lo_u32 v2, v4, v5
	v_mul_hi_u32 v2, v5, v2
	v_add_u32_e32 v2, v5, v2
	v_mul_hi_u32 v2, v6, v2
	v_mul_lo_u32 v4, v2, v3
	v_sub_u32_e32 v4, v6, v4
	v_add_u32_e32 v5, 1, v2
	v_cmp_ge_u32_e32 vcc, v4, v3
	s_nop 1
	v_cndmask_b32_e32 v2, v2, v5, vcc
	v_sub_u32_e32 v5, v4, v3
	v_cndmask_b32_e32 v4, v4, v5, vcc
	v_add_u32_e32 v5, 1, v2
	v_cmp_ge_u32_e32 vcc, v4, v3
	v_add_u32_e32 v4, 1, v6
	s_nop 0
	v_cndmask_b32_e32 v2, v2, v5, vcc
	v_mul_lo_u32 v5, v3, v2
	v_add_u32_e32 v3, v5, v3
	v_cmp_ne_u32_e32 vcc, v4, v3
	s_and_saveexec_b64 s[18:19], vcc
	s_xor_b64 s[22:23], exec, s[18:19]
	s_cbranch_execz .LBB0_153
	s_waitcnt lgkmcnt(0)
	v_mov_b32_e32 v1, 0x23fe4
	ds_read_b32 v1, v1
	v_add_u32_e32 v2, 1, v2
	s_waitcnt lgkmcnt(0)
	v_mul_lo_u32 v2, v2, v1
	v_mov_b32_e32 v1, 0x3400
	global_load_dword v1, v1, s[30:31] sc1
	s_add_u32 s26, s30, 0x3400
	s_addc_u32 s27, s31, 0
	s_waitcnt vmcnt(0)
	v_cmp_lt_u32_e32 vcc, v1, v2
	s_and_saveexec_b64 s[24:25], vcc
	s_cbranch_execz .LBB0_152
	s_mov_b32 s3, 1
	s_mov_b64 s[46:47], 0
	v_mov_b32_e32 v1, 0
	s_branch .LBB0_143

; __device__ __forceinline__ unsigned xb_ld(unsigned* p)              { return __hip_atomic_load(p, __ATOMIC_RELAXED, __HIP_MEMORY_SCOPE_AGENT); }
; #define XB_SPIN(cond, bar) do { unsigned _sp = 0; while (cond) { __builtin_amdgcn_s_sleep(1); \
;     if ((++_sp & 255u) == 0u) { if (xb_ld(&(bar)[XB_TMO])) break; if (_sp > XB_SPIN_CAP) { atomicAdd(&(bar)[XB_TMO], 1u); break; } } } } while (0)
; __device__ __forceinline__ void xcd_barrier(const XcdBarrier& b) {
;     ...
;             XB_SPIN(xb_ld(&bar[XB_XGEN(b.x)]) == gen, bar);
.LBB0_145:
	global_load_dword v3, v1, s[26:27] sc1
	s_add_i32 s3, s3, 1
	s_mov_b64 s[64:65], -1
	s_waitcnt vmcnt(0)
	v_cmp_ge_u32_e32 vcc, v3, v2
	s_orn2_b64 s[62:63], vcc, exec
	s_branch .LBB0_142

; __device__ __forceinline__ unsigned xb_ld(unsigned* p)              { return __hip_atomic_load(p, __ATOMIC_RELAXED, __HIP_MEMORY_SCOPE_AGENT); }
; __device__ __forceinline__ unsigned xb_add(unsigned* p, unsigned v) { return __hip_atomic_fetch_add(p, v, __ATOMIC_RELAXED, __HIP_MEMORY_SCOPE_AGENT); }
; #define XB_SPIN(cond, bar) do { unsigned _sp = 0; while (cond) { __builtin_amdgcn_s_sleep(1); \
;     if ((++_sp & 255u) == 0u) { if (xb_ld(&(bar)[XB_TMO])) break; if (_sp > XB_SPIN_CAP) { atomicAdd(&(bar)[XB_TMO], 1u); break; } } } } while (0)
; __device__ __forceinline__ void xcd_barrier(const XcdBarrier& b) {
;     ...
;             const unsigned og = xb_add(&bar[XB_TOP], 1u);
;             const unsigned tg = og / nx;
;             if (og + 1u == (tg + 1u) * nx) xb_add(&bar[XB_TOPGEN], 1u);
;             else XB_SPIN(xb_ld(&bar[XB_TOPGEN]) == tg, bar);
.LBB0_156:
	s_or_b64 exec, exec, s[24:25]
	v_cvt_f32_u32_e32 v4, v1
	s_waitcnt vmcnt(0)
	v_readfirstlane_b32 s3, v3
	s_add_u32 s24, s30, 0x3500
	s_addc_u32 s25, s31, 0
	v_rcp_iflag_f32_e32 v4, v4
	v_add_u32_e32 v2, s3, v2
	v_add_u32_e32 v5, 1, v2
	s_mov_b64 s[26:27], -1
	v_mul_f32_e32 v3, 0x4f7ffffe, v4
	v_cvt_u32_f32_e32 v3, v3
	v_sub_u32_e32 v4, 0, v1
	v_mul_lo_u32 v4, v4, v3
	v_mul_hi_u32 v4, v3, v4
	v_add_u32_e32 v3, v3, v4
	v_mul_hi_u32 v3, v2, v3
	v_mul_lo_u32 v4, v3, v1
	v_sub_u32_e32 v2, v2, v4
	v_add_u32_e32 v6, 1, v3
	v_cmp_ge_u32_e32 vcc, v2, v1
	v_sub_u32_e32 v4, v2, v1
	s_nop 0
	v_cndmask_b32_e32 v3, v3, v6, vcc
	v_cndmask_b32_e32 v2, v2, v4, vcc
	v_add_u32_e32 v4, 1, v3
	v_cmp_ge_u32_e32 vcc, v2, v1
	s_nop 1
	v_cndmask_b32_e32 v4, v3, v4, vcc
	v_mul_lo_u32 v2, v1, v4
	v_add_u32_e32 v1, v2, v1
	v_cmp_ne_u32_e32 vcc, v5, v1
	v_mov_b64_e32 v[2:3], s[24:25]
	s_and_saveexec_b64 s[22:23], vcc
	s_cbranch_execz .LBB0_168
	v_mov_b32_e32 v2, 0x23fe4
	ds_read_b32 v2, v2
	v_add_u32_e32 v4, 1, v4
	s_waitcnt lgkmcnt(0)
	v_mul_lo_u32 v4, v4, v2
	v_mov_b32_e32 v1, 0
	global_load_dword v2, v1, s[24:25] offset:-256 sc1
	s_mov_b64 s[60:61], 0
	s_waitcnt vmcnt(0)
	v_cmp_lt_u32_e32 vcc, v2, v4
	s_and_saveexec_b64 s[46:47], vcc
	s_cbranch_execz .LBB0_167
	s_add_u32 s26, s30, 0x200
	s_addc_u32 s27, s31, 0
	s_mov_b32 s3, 1
	s_branch .LBB0_160

; __device__ __forceinline__ unsigned xb_ld(unsigned* p)              { return __hip_atomic_load(p, __ATOMIC_RELAXED, __HIP_MEMORY_SCOPE_AGENT); }
; #define XB_SPIN(cond, bar) do { unsigned _sp = 0; while (cond) { __builtin_amdgcn_s_sleep(1); \
;     if ((++_sp & 255u) == 0u) { if (xb_ld(&(bar)[XB_TMO])) break; if (_sp > XB_SPIN_CAP) { atomicAdd(&(bar)[XB_TMO], 1u); break; } } } } while (0)
; __device__ __forceinline__ void xcd_barrier(const XcdBarrier& b) {
;     ...
;             else XB_SPIN(xb_ld(&bar[XB_TOPGEN]) == tg, bar);
.LBB0_162:
	global_load_dword v2, v1, s[24:25] offset:-256 sc1
	s_add_i32 s3, s3, 1
	s_mov_b64 s[64:65], -1
	s_waitcnt vmcnt(0)
	v_cmp_ge_u32_e32 vcc, v2, v4
	s_orn2_b64 s[70:71], vcc, exec
	s_branch .LBB0_159

; __device__ __forceinline__ unsigned xb_add(unsigned* p, unsigned v) { return __hip_atomic_fetch_add(p, v, __ATOMIC_RELAXED, __HIP_MEMORY_SCOPE_AGENT); }
; __device__ __forceinline__ void xcd_barrier(const XcdBarrier& b) {
;     ...
;             __builtin_amdgcn_fence(__ATOMIC_ACQUIRE, "agent");
;             xb_add(&bar[XB_XGEN(b.x)], 1u);
;             asm volatile("s_waitcnt vmcnt(0)" ::: "memory");
.LBB0_170:
	s_or_b64 exec, exec, s[22:23]
	s_mov_b64 s[22:23], exec
	v_mbcnt_lo_u32_b32 v1, s22, 0
	v_mbcnt_hi_u32_b32 v1, s23, v1
	v_cmp_eq_u32_e32 vcc, 0, v1
	s_waitcnt vmcnt(0)
	buffer_inv sc1
	s_and_saveexec_b64 s[24:25], vcc
	s_cbranch_execz .LBB0_172
	s_bcnt1_i32_b64 s3, s[22:23]
	v_mov_b32_e32 v1, 0x2000
	v_mov_b32_e32 v2, s3
.LBB0_172:
	s_or_b64 exec, exec, s[24:25]
	s_waitcnt vmcnt(0)

; __device__ __forceinline__ unsigned xb_ld(unsigned* p)              { return __hip_atomic_load(p, __ATOMIC_RELAXED, __HIP_MEMORY_SCOPE_AGENT); }
; __device__ __forceinline__ unsigned xb_add(unsigned* p, unsigned v) { return __hip_atomic_fetch_add(p, v, __ATOMIC_RELAXED, __HIP_MEMORY_SCOPE_AGENT); }
; #define XB_SPIN(cond, bar) do { unsigned _sp = 0; while (cond) { __builtin_amdgcn_s_sleep(1); \
;     if ((++_sp & 255u) == 0u) { if (xb_ld(&(bar)[XB_TMO])) break; if (_sp > XB_SPIN_CAP) { atomicAdd(&(bar)[XB_TMO], 1u); break; } } } } while (0)
; __device__ __forceinline__ void xcd_barrier(const XcdBarrier& b) {
;     ...
;         const unsigned old = xb_add(&bar[XB_XSUB(b.x)], 1u);
;         const unsigned gen = old / nloc;
;         if (old + 1u == (gen + 1u) * nloc) {
;             __builtin_amdgcn_fence(__ATOMIC_RELEASE, "agent");
;             asm volatile("s_waitcnt vmcnt(0)" ::: "memory");
;             const unsigned og = xb_add(&bar[XB_TOP], 1u);
;             const unsigned tg = og / nx;
;             if (og + 1u == (tg + 1u) * nx) xb_add(&bar[XB_TOPGEN], 1u);
;             else XB_SPIN(xb_ld(&bar[XB_TOPGEN]) == tg, bar);
;             __builtin_amdgcn_fence(__ATOMIC_ACQUIRE, "agent");
;             xb_add(&bar[XB_XGEN(b.x)], 1u);
;             asm volatile("s_waitcnt vmcnt(0)" ::: "memory");
;         } else {
;             XB_SPIN(xb_ld(&bar[XB_XGEN(b.x)]) == gen, bar);
.LBB0_206:
	s_or_b64 exec, exec, s[12:13]
	v_cvt_f32_u32_e32 v4, v2
	s_waitcnt vmcnt(0)
	v_readfirstlane_b32 s10, v3
	v_sub_u32_e32 v3, 0, v2
	v_rcp_iflag_f32_e32 v4, v4
	v_add_u32_e32 v5, s10, v1
	v_mul_f32_e32 v4, 0x4f7ffffe, v4
	v_cvt_u32_f32_e32 v4, v4
	v_mul_lo_u32 v1, v3, v4
	v_mul_hi_u32 v1, v4, v1
	v_add_u32_e32 v1, v4, v1
	v_mul_hi_u32 v1, v5, v1
	v_mul_lo_u32 v3, v1, v2
	v_sub_u32_e32 v3, v5, v3
	v_add_u32_e32 v4, 1, v1
	v_cmp_ge_u32_e32 vcc, v3, v2
	s_nop 1
	v_cndmask_b32_e32 v1, v1, v4, vcc
	v_sub_u32_e32 v4, v3, v2
	v_cndmask_b32_e32 v3, v3, v4, vcc
	v_add_u32_e32 v4, 1, v1
	v_cmp_ge_u32_e32 vcc, v3, v2
	v_add_u32_e32 v3, 1, v5
	s_nop 0
	v_cndmask_b32_e32 v1, v1, v4, vcc
	v_mul_lo_u32 v4, v2, v1
	v_add_u32_e32 v2, v4, v2
	v_cmp_ne_u32_e32 vcc, v3, v2
	s_and_saveexec_b64 s[10:11], vcc
	s_xor_b64 s[10:11], exec, s[10:11]
	s_cbranch_execz .LBB0_220
	s_waitcnt lgkmcnt(0)
	v_mov_b32_e32 v0, 0x23fe4
	ds_read_b32 v0, v0
	v_add_u32_e32 v1, 1, v1
	s_waitcnt lgkmcnt(0)
	v_mul_lo_u32 v1, v1, v0
	v_mov_b32_e32 v0, 0x3400
	global_load_dword v0, v0, s[30:31] sc1
	s_add_u32 s14, s30, 0x3400
	s_addc_u32 s15, s31, 0
	s_waitcnt vmcnt(0)
	v_cmp_lt_u32_e32 vcc, v0, v1
	s_and_saveexec_b64 s[12:13], vcc
	s_cbranch_execz .LBB0_219
	s_mov_b32 s18, 1
	s_mov_b64 s[26:27], 0
	v_mov_b32_e32 v0, 0
	s_branch .LBB0_210

; __device__ __forceinline__ unsigned xb_ld(unsigned* p)              { return __hip_atomic_load(p, __ATOMIC_RELAXED, __HIP_MEMORY_SCOPE_AGENT); }
; #define XB_SPIN(cond, bar) do { unsigned _sp = 0; while (cond) { __builtin_amdgcn_s_sleep(1); \
;     if ((++_sp & 255u) == 0u) { if (xb_ld(&(bar)[XB_TMO])) break; if (_sp > XB_SPIN_CAP) { atomicAdd(&(bar)[XB_TMO], 1u); break; } } } } while (0)
; __device__ __forceinline__ void xcd_barrier(const XcdBarrier& b) {
;     ...
;             XB_SPIN(xb_ld(&bar[XB_XGEN(b.x)]) == gen, bar);
.LBB0_212:
	global_load_dword v2, v0, s[14:15] sc1
	s_add_i32 s18, s18, 1
	s_mov_b64 s[62:63], -1
	s_waitcnt vmcnt(0)
	v_cmp_ge_u32_e32 vcc, v2, v1
	s_orn2_b64 s[60:61], vcc, exec
	s_branch .LBB0_209

; __device__ __forceinline__ unsigned xb_ld(unsigned* p)              { return __hip_atomic_load(p, __ATOMIC_RELAXED, __HIP_MEMORY_SCOPE_AGENT); }
; __device__ __forceinline__ unsigned xb_add(unsigned* p, unsigned v) { return __hip_atomic_fetch_add(p, v, __ATOMIC_RELAXED, __HIP_MEMORY_SCOPE_AGENT); }
; #define XB_SPIN(cond, bar) do { unsigned _sp = 0; while (cond) { __builtin_amdgcn_s_sleep(1); \
;     if ((++_sp & 255u) == 0u) { if (xb_ld(&(bar)[XB_TMO])) break; if (_sp > XB_SPIN_CAP) { atomicAdd(&(bar)[XB_TMO], 1u); break; } } } } while (0)
; __device__ __forceinline__ void xcd_barrier(const XcdBarrier& b) {
;     ...
;             const unsigned og = xb_add(&bar[XB_TOP], 1u);
;             const unsigned tg = og / nx;
;             if (og + 1u == (tg + 1u) * nx) xb_add(&bar[XB_TOPGEN], 1u);
;             else XB_SPIN(xb_ld(&bar[XB_TOPGEN]) == tg, bar);
.LBB0_223:
	s_or_b64 exec, exec, s[12:13]
	v_cvt_f32_u32_e32 v3, v0
	s_waitcnt vmcnt(0)
	v_readfirstlane_b32 s10, v2
	s_add_u32 s12, s30, 0x3500
	s_addc_u32 s13, s31, 0
	v_rcp_iflag_f32_e32 v3, v3
	v_add_u32_e32 v1, s10, v1
	v_add_u32_e32 v4, 1, v1
	s_mov_b64 s[14:15], -1
	v_mul_f32_e32 v2, 0x4f7ffffe, v3
	v_cvt_u32_f32_e32 v2, v2
	v_sub_u32_e32 v3, 0, v0
	v_mul_lo_u32 v3, v3, v2
	v_mul_hi_u32 v3, v2, v3
	v_add_u32_e32 v2, v2, v3
	v_mul_hi_u32 v2, v1, v2
	v_mul_lo_u32 v3, v2, v0
	v_sub_u32_e32 v1, v1, v3
	v_add_u32_e32 v5, 1, v2
	v_cmp_ge_u32_e32 vcc, v1, v0
	v_sub_u32_e32 v3, v1, v0
	s_nop 0
	v_cndmask_b32_e32 v2, v2, v5, vcc
	v_cndmask_b32_e32 v1, v1, v3, vcc
	v_add_u32_e32 v3, 1, v2
	v_cmp_ge_u32_e32 vcc, v1, v0
	s_nop 1
	v_cndmask_b32_e32 v2, v2, v3, vcc
	v_mul_lo_u32 v1, v0, v2
	v_add_u32_e32 v0, v1, v0
	v_cmp_ne_u32_e32 vcc, v4, v0
	v_mov_b64_e32 v[0:1], s[12:13]
	s_and_saveexec_b64 s[10:11], vcc
	s_cbranch_execz .LBB0_235
	v_mov_b32_e32 v1, 0x23fe4
	ds_read_b32 v1, v1
	v_add_u32_e32 v2, 1, v2
	s_waitcnt lgkmcnt(0)
	v_mul_lo_u32 v2, v2, v1
	v_mov_b32_e32 v0, 0
	global_load_dword v1, v0, s[12:13] offset:-256 sc1
	s_mov_b64 s[48:49], 0
	s_waitcnt vmcnt(0)
	v_cmp_lt_u32_e32 vcc, v1, v2
	s_and_saveexec_b64 s[26:27], vcc
	s_cbranch_execz .LBB0_234
	s_add_u32 s14, s30, 0x200
	s_addc_u32 s15, s31, 0
	s_mov_b32 s18, 1
	s_branch .LBB0_227

; __device__ __forceinline__ unsigned xb_ld(unsigned* p)              { return __hip_atomic_load(p, __ATOMIC_RELAXED, __HIP_MEMORY_SCOPE_AGENT); }
; #define XB_SPIN(cond, bar) do { unsigned _sp = 0; while (cond) { __builtin_amdgcn_s_sleep(1); \
;     if ((++_sp & 255u) == 0u) { if (xb_ld(&(bar)[XB_TMO])) break; if (_sp > XB_SPIN_CAP) { atomicAdd(&(bar)[XB_TMO], 1u); break; } } } } while (0)
; __device__ __forceinline__ void xcd_barrier(const XcdBarrier& b) {
;     ...
;             else XB_SPIN(xb_ld(&bar[XB_TOPGEN]) == tg, bar);
.LBB0_229:
	global_load_dword v1, v0, s[12:13] offset:-256 sc1
	s_add_i32 s18, s18, 1
	s_mov_b64 s[62:63], -1
	s_waitcnt vmcnt(0)
	v_cmp_ge_u32_e32 vcc, v1, v2
	s_orn2_b64 s[68:69], vcc, exec
	s_branch .LBB0_226

; __device__ __forceinline__ unsigned xb_add(unsigned* p, unsigned v) { return __hip_atomic_fetch_add(p, v, __ATOMIC_RELAXED, __HIP_MEMORY_SCOPE_AGENT); }
; __device__ __forceinline__ void xcd_barrier(const XcdBarrier& b) {
;     ...
;             __builtin_amdgcn_fence(__ATOMIC_ACQUIRE, "agent");
;             xb_add(&bar[XB_XGEN(b.x)], 1u);
;             asm volatile("s_waitcnt vmcnt(0)" ::: "memory");
.LBB0_237:
	s_or_b64 exec, exec, s[10:11]
	s_mov_b64 s[10:11], exec
	v_mbcnt_lo_u32_b32 v0, s10, 0
	v_mbcnt_hi_u32_b32 v0, s11, v0
	v_cmp_eq_u32_e32 vcc, 0, v0
	s_waitcnt vmcnt(0)
	buffer_inv sc1
	s_and_saveexec_b64 s[12:13], vcc
	s_cbranch_execz .LBB0_239
	s_bcnt1_i32_b64 s10, s[10:11]
	v_mov_b32_e32 v0, 0x2000
	v_mov_b32_e32 v1, s10
.LBB0_239:
	s_or_b64 exec, exec, s[12:13]
	s_waitcnt vmcnt(0)

; __device__ __forceinline__ unsigned xb_ld(unsigned* p)              { return __hip_atomic_load(p, __ATOMIC_RELAXED, __HIP_MEMORY_SCOPE_AGENT); }
; __device__ __forceinline__ unsigned xb_add(unsigned* p, unsigned v) { return __hip_atomic_fetch_add(p, v, __ATOMIC_RELAXED, __HIP_MEMORY_SCOPE_AGENT); }
; #define XB_SPIN(cond, bar) do { unsigned _sp = 0; while (cond) { __builtin_amdgcn_s_sleep(1); \
;     if ((++_sp & 255u) == 0u) { if (xb_ld(&(bar)[XB_TMO])) break; if (_sp > XB_SPIN_CAP) { atomicAdd(&(bar)[XB_TMO], 1u); break; } } } } while (0)
; __device__ __forceinline__ void xcd_barrier(const XcdBarrier& b) {
;     ...
;         const unsigned old = xb_add(&bar[XB_XSUB(b.x)], 1u);
;         const unsigned gen = old / nloc;
;         if (old + 1u == (gen + 1u) * nloc) {
;             __builtin_amdgcn_fence(__ATOMIC_RELEASE, "agent");
;             asm volatile("s_waitcnt vmcnt(0)" ::: "memory");
;             const unsigned og = xb_add(&bar[XB_TOP], 1u);
;             const unsigned tg = og / nx;
;             if (og + 1u == (tg + 1u) * nx) xb_add(&bar[XB_TOPGEN], 1u);
;             else XB_SPIN(xb_ld(&bar[XB_TOPGEN]) == tg, bar);
;             __builtin_amdgcn_fence(__ATOMIC_ACQUIRE, "agent");
;             xb_add(&bar[XB_XGEN(b.x)], 1u);
;             asm volatile("s_waitcnt vmcnt(0)" ::: "memory");
;         } else {
;             XB_SPIN(xb_ld(&bar[XB_XGEN(b.x)]) == gen, bar);
.LBB0_307:
	s_or_b64 exec, exec, s[12:13]
	v_cvt_f32_u32_e32 v4, v2
	s_waitcnt vmcnt(0)
	v_readfirstlane_b32 s10, v3
	v_sub_u32_e32 v3, 0, v2
	v_rcp_iflag_f32_e32 v4, v4
	v_add_u32_e32 v5, s10, v1
	v_mul_f32_e32 v4, 0x4f7ffffe, v4
	v_cvt_u32_f32_e32 v4, v4
	v_mul_lo_u32 v1, v3, v4
	v_mul_hi_u32 v1, v4, v1
	v_add_u32_e32 v1, v4, v1
	v_mul_hi_u32 v1, v5, v1
	v_mul_lo_u32 v3, v1, v2
	v_sub_u32_e32 v3, v5, v3
	v_add_u32_e32 v4, 1, v1
	v_cmp_ge_u32_e32 vcc, v3, v2
	s_nop 1
	v_cndmask_b32_e32 v1, v1, v4, vcc
	v_sub_u32_e32 v4, v3, v2
	v_cndmask_b32_e32 v3, v3, v4, vcc
	v_add_u32_e32 v4, 1, v1
	v_cmp_ge_u32_e32 vcc, v3, v2
	v_add_u32_e32 v3, 1, v5
	s_nop 0
	v_cndmask_b32_e32 v1, v1, v4, vcc
	v_mul_lo_u32 v4, v2, v1
	v_add_u32_e32 v2, v4, v2
	v_cmp_ne_u32_e32 vcc, v3, v2
	s_and_saveexec_b64 s[10:11], vcc
	s_xor_b64 s[10:11], exec, s[10:11]
	s_cbranch_execz .LBB0_321
	s_waitcnt lgkmcnt(0)
	v_mov_b32_e32 v0, 0x23fe4
	ds_read_b32 v0, v0
	v_add_u32_e32 v1, 1, v1
	s_waitcnt lgkmcnt(0)
	v_mul_lo_u32 v1, v1, v0
	v_mov_b32_e32 v0, 0x3400
	global_load_dword v0, v0, s[30:31] sc1
	s_add_u32 s14, s30, 0x3400
	s_addc_u32 s15, s31, 0
	s_waitcnt vmcnt(0)
	v_cmp_lt_u32_e32 vcc, v0, v1
	s_and_saveexec_b64 s[12:13], vcc
	s_cbranch_execz .LBB0_320
	s_mov_b32 s18, 1
	s_mov_b64 s[60:61], 0
	v_mov_b32_e32 v0, 0
	s_branch .LBB0_311

; __device__ __forceinline__ unsigned xb_ld(unsigned* p)              { return __hip_atomic_load(p, __ATOMIC_RELAXED, __HIP_MEMORY_SCOPE_AGENT); }
; #define XB_SPIN(cond, bar) do { unsigned _sp = 0; while (cond) { __builtin_amdgcn_s_sleep(1); \
;     if ((++_sp & 255u) == 0u) { if (xb_ld(&(bar)[XB_TMO])) break; if (_sp > XB_SPIN_CAP) { atomicAdd(&(bar)[XB_TMO], 1u); break; } } } } while (0)
; __device__ __forceinline__ void xcd_barrier(const XcdBarrier& b) {
;     ...
;             XB_SPIN(xb_ld(&bar[XB_XGEN(b.x)]) == gen, bar);
.LBB0_313:
	global_load_dword v2, v0, s[14:15] sc1
	s_add_i32 s18, s18, 1
	s_mov_b64 s[68:69], -1
	s_waitcnt vmcnt(0)
	v_cmp_ge_u32_e32 vcc, v2, v1
	s_orn2_b64 s[64:65], vcc, exec
	s_branch .LBB0_310

; __device__ __forceinline__ unsigned xb_ld(unsigned* p)              { return __hip_atomic_load(p, __ATOMIC_RELAXED, __HIP_MEMORY_SCOPE_AGENT); }
; __device__ __forceinline__ unsigned xb_add(unsigned* p, unsigned v) { return __hip_atomic_fetch_add(p, v, __ATOMIC_RELAXED, __HIP_MEMORY_SCOPE_AGENT); }
; #define XB_SPIN(cond, bar) do { unsigned _sp = 0; while (cond) { __builtin_amdgcn_s_sleep(1); \
;     if ((++_sp & 255u) == 0u) { if (xb_ld(&(bar)[XB_TMO])) break; if (_sp > XB_SPIN_CAP) { atomicAdd(&(bar)[XB_TMO], 1u); break; } } } } while (0)
; __device__ __forceinline__ void xcd_barrier(const XcdBarrier& b) {
;     ...
;             const unsigned og = xb_add(&bar[XB_TOP], 1u);
;             const unsigned tg = og / nx;
;             if (og + 1u == (tg + 1u) * nx) xb_add(&bar[XB_TOPGEN], 1u);
;             else XB_SPIN(xb_ld(&bar[XB_TOPGEN]) == tg, bar);
.LBB0_324:
	s_or_b64 exec, exec, s[12:13]
	v_cvt_f32_u32_e32 v3, v0
	s_waitcnt vmcnt(0)
	v_readfirstlane_b32 s10, v2
	s_add_u32 s12, s30, 0x3500
	s_addc_u32 s13, s31, 0
	v_rcp_iflag_f32_e32 v3, v3
	v_add_u32_e32 v1, s10, v1
	v_add_u32_e32 v4, 1, v1
	s_mov_b64 s[14:15], -1
	v_mul_f32_e32 v2, 0x4f7ffffe, v3
	v_cvt_u32_f32_e32 v2, v2
	v_sub_u32_e32 v3, 0, v0
	v_mul_lo_u32 v3, v3, v2
	v_mul_hi_u32 v3, v2, v3
	v_add_u32_e32 v2, v2, v3
	v_mul_hi_u32 v2, v1, v2
	v_mul_lo_u32 v3, v2, v0
	v_sub_u32_e32 v1, v1, v3
	v_add_u32_e32 v5, 1, v2
	v_cmp_ge_u32_e32 vcc, v1, v0
	v_sub_u32_e32 v3, v1, v0
	s_nop 0
	v_cndmask_b32_e32 v2, v2, v5, vcc
	v_cndmask_b32_e32 v1, v1, v3, vcc
	v_add_u32_e32 v3, 1, v2
	v_cmp_ge_u32_e32 vcc, v1, v0
	s_nop 1
	v_cndmask_b32_e32 v2, v2, v3, vcc
	v_mul_lo_u32 v1, v0, v2
	v_add_u32_e32 v0, v1, v0
	v_cmp_ne_u32_e32 vcc, v4, v0
	v_mov_b64_e32 v[0:1], s[12:13]
	s_and_saveexec_b64 s[10:11], vcc
	s_cbranch_execz .LBB0_336
	v_mov_b32_e32 v1, 0x23fe4
	ds_read_b32 v1, v1
	v_add_u32_e32 v2, 1, v2
	s_waitcnt lgkmcnt(0)
	v_mul_lo_u32 v2, v2, v1
	v_mov_b32_e32 v0, 0
	global_load_dword v1, v0, s[12:13] offset:-256 sc1
	s_mov_b64 s[62:63], 0
	s_waitcnt vmcnt(0)
	v_cmp_lt_u32_e32 vcc, v1, v2
	s_and_saveexec_b64 s[60:61], vcc
	s_cbranch_execz .LBB0_335
	s_add_u32 s14, s30, 0x200
	s_addc_u32 s15, s31, 0
	s_mov_b32 s18, 1
	s_branch .LBB0_328

; __device__ __forceinline__ unsigned xb_ld(unsigned* p)              { return __hip_atomic_load(p, __ATOMIC_RELAXED, __HIP_MEMORY_SCOPE_AGENT); }
; #define XB_SPIN(cond, bar) do { unsigned _sp = 0; while (cond) { __builtin_amdgcn_s_sleep(1); \
;     if ((++_sp & 255u) == 0u) { if (xb_ld(&(bar)[XB_TMO])) break; if (_sp > XB_SPIN_CAP) { atomicAdd(&(bar)[XB_TMO], 1u); break; } } } } while (0)
; __device__ __forceinline__ void xcd_barrier(const XcdBarrier& b) {
;     ...
;             else XB_SPIN(xb_ld(&bar[XB_TOPGEN]) == tg, bar);
.LBB0_330:
	global_load_dword v1, v0, s[12:13] offset:-256 sc1
	s_add_i32 s18, s18, 1
	s_mov_b64 s[68:69], -1
	s_waitcnt vmcnt(0)
	v_cmp_ge_u32_e32 vcc, v1, v2
	s_orn2_b64 s[72:73], vcc, exec
	s_branch .LBB0_327

; __device__ __forceinline__ unsigned xb_add(unsigned* p, unsigned v) { return __hip_atomic_fetch_add(p, v, __ATOMIC_RELAXED, __HIP_MEMORY_SCOPE_AGENT); }
; __device__ __forceinline__ void xcd_barrier(const XcdBarrier& b) {
;     ...
;             __builtin_amdgcn_fence(__ATOMIC_ACQUIRE, "agent");
;             xb_add(&bar[XB_XGEN(b.x)], 1u);
;             asm volatile("s_waitcnt vmcnt(0)" ::: "memory");
.LBB0_338:
	s_or_b64 exec, exec, s[10:11]
	s_mov_b64 s[10:11], exec
	v_mbcnt_lo_u32_b32 v0, s10, 0
	v_mbcnt_hi_u32_b32 v0, s11, v0
	v_cmp_eq_u32_e32 vcc, 0, v0
	s_waitcnt vmcnt(0)
	buffer_inv sc1
	s_and_saveexec_b64 s[12:13], vcc
	s_cbranch_execz .LBB0_340
	s_bcnt1_i32_b64 s10, s[10:11]
	v_mov_b32_e32 v0, 0x2000
	v_mov_b32_e32 v1, s10
.LBB0_340:
	s_or_b64 exec, exec, s[12:13]
	s_waitcnt vmcnt(0)

; __device__ __forceinline__ unsigned xb_ld(unsigned* p)              { return __hip_atomic_load(p, __ATOMIC_RELAXED, __HIP_MEMORY_SCOPE_AGENT); }
; __device__ __forceinline__ unsigned xb_add(unsigned* p, unsigned v) { return __hip_atomic_fetch_add(p, v, __ATOMIC_RELAXED, __HIP_MEMORY_SCOPE_AGENT); }
; #define XB_SPIN(cond, bar) do { unsigned _sp = 0; while (cond) { __builtin_amdgcn_s_sleep(1); \
;     if ((++_sp & 255u) == 0u) { if (xb_ld(&(bar)[XB_TMO])) break; if (_sp > XB_SPIN_CAP) { atomicAdd(&(bar)[XB_TMO], 1u); break; } } } } while (0)
; __device__ __forceinline__ void xcd_barrier(const XcdBarrier& b) {
;     ...
;         const unsigned old = xb_add(&bar[XB_XSUB(b.x)], 1u);
;         const unsigned gen = old / nloc;
;         if (old + 1u == (gen + 1u) * nloc) {
;             __builtin_amdgcn_fence(__ATOMIC_RELEASE, "agent");
;             asm volatile("s_waitcnt vmcnt(0)" ::: "memory");
;             const unsigned og = xb_add(&bar[XB_TOP], 1u);
;             const unsigned tg = og / nx;
;             if (og + 1u == (tg + 1u) * nx) xb_add(&bar[XB_TOPGEN], 1u);
;             else XB_SPIN(xb_ld(&bar[XB_TOPGEN]) == tg, bar);
;             __builtin_amdgcn_fence(__ATOMIC_ACQUIRE, "agent");
;             xb_add(&bar[XB_XGEN(b.x)], 1u);
;             asm volatile("s_waitcnt vmcnt(0)" ::: "memory");
;         } else {
;             XB_SPIN(xb_ld(&bar[XB_XGEN(b.x)]) == gen, bar);
.LBB0_389:
	s_or_b64 exec, exec, s[8:9]
	v_cvt_f32_u32_e32 v4, v2
	s_waitcnt vmcnt(0)
	v_readfirstlane_b32 s6, v3
	v_sub_u32_e32 v3, 0, v2
	v_rcp_iflag_f32_e32 v4, v4
	v_add_u32_e32 v5, s6, v1
	v_mul_f32_e32 v4, 0x4f7ffffe, v4
	v_cvt_u32_f32_e32 v4, v4
	v_mul_lo_u32 v1, v3, v4
	v_mul_hi_u32 v1, v4, v1
	v_add_u32_e32 v1, v4, v1
	v_mul_hi_u32 v1, v5, v1
	v_mul_lo_u32 v3, v1, v2
	v_sub_u32_e32 v3, v5, v3
	v_add_u32_e32 v4, 1, v1
	v_cmp_ge_u32_e32 vcc, v3, v2
	s_nop 1
	v_cndmask_b32_e32 v1, v1, v4, vcc
	v_sub_u32_e32 v4, v3, v2
	v_cndmask_b32_e32 v3, v3, v4, vcc
	v_add_u32_e32 v4, 1, v1
	v_cmp_ge_u32_e32 vcc, v3, v2
	v_add_u32_e32 v3, 1, v5
	s_nop 0
	v_cndmask_b32_e32 v1, v1, v4, vcc
	v_mul_lo_u32 v4, v2, v1
	v_add_u32_e32 v2, v4, v2
	v_cmp_ne_u32_e32 vcc, v3, v2
	s_and_saveexec_b64 s[6:7], vcc
	s_xor_b64 s[6:7], exec, s[6:7]
	s_cbranch_execz .LBB0_403
	s_waitcnt lgkmcnt(0)
	v_mov_b32_e32 v0, 0x23fe4
	ds_read_b32 v0, v0
	v_add_u32_e32 v1, 1, v1
	s_waitcnt lgkmcnt(0)
	v_mul_lo_u32 v1, v1, v0
	v_mov_b32_e32 v0, 0x3400
	global_load_dword v0, v0, s[30:31] sc1
	s_add_u32 s10, s30, 0x3400
	s_addc_u32 s11, s31, 0
	s_waitcnt vmcnt(0)
	v_cmp_lt_u32_e32 vcc, v0, v1
	s_and_saveexec_b64 s[8:9], vcc
	s_cbranch_execz .LBB0_402
	s_mov_b32 s16, 1
	s_mov_b64 s[12:13], 0
	v_mov_b32_e32 v0, 0
	s_branch .LBB0_393

; __device__ __forceinline__ unsigned xb_ld(unsigned* p)              { return __hip_atomic_load(p, __ATOMIC_RELAXED, __HIP_MEMORY_SCOPE_AGENT); }
; #define XB_SPIN(cond, bar) do { unsigned _sp = 0; while (cond) { __builtin_amdgcn_s_sleep(1); \
;     if ((++_sp & 255u) == 0u) { if (xb_ld(&(bar)[XB_TMO])) break; if (_sp > XB_SPIN_CAP) { atomicAdd(&(bar)[XB_TMO], 1u); break; } } } } while (0)
; __device__ __forceinline__ void xcd_barrier(const XcdBarrier& b) {
;     ...
;             XB_SPIN(xb_ld(&bar[XB_XGEN(b.x)]) == gen, bar);
.LBB0_395:
	global_load_dword v2, v0, s[10:11] sc1
	s_add_i32 s16, s16, 1
	s_mov_b64 s[62:63], -1
	s_waitcnt vmcnt(0)
	v_cmp_ge_u32_e32 vcc, v2, v1
	s_orn2_b64 s[40:41], vcc, exec
	s_branch .LBB0_392

; __device__ __forceinline__ unsigned xb_ld(unsigned* p)              { return __hip_atomic_load(p, __ATOMIC_RELAXED, __HIP_MEMORY_SCOPE_AGENT); }
; __device__ __forceinline__ unsigned xb_add(unsigned* p, unsigned v) { return __hip_atomic_fetch_add(p, v, __ATOMIC_RELAXED, __HIP_MEMORY_SCOPE_AGENT); }
; #define XB_SPIN(cond, bar) do { unsigned _sp = 0; while (cond) { __builtin_amdgcn_s_sleep(1); \
;     if ((++_sp & 255u) == 0u) { if (xb_ld(&(bar)[XB_TMO])) break; if (_sp > XB_SPIN_CAP) { atomicAdd(&(bar)[XB_TMO], 1u); break; } } } } while (0)
; __device__ __forceinline__ void xcd_barrier(const XcdBarrier& b) {
;     ...
;             const unsigned og = xb_add(&bar[XB_TOP], 1u);
;             const unsigned tg = og / nx;
;             if (og + 1u == (tg + 1u) * nx) xb_add(&bar[XB_TOPGEN], 1u);
;             else XB_SPIN(xb_ld(&bar[XB_TOPGEN]) == tg, bar);
.LBB0_406:
	s_or_b64 exec, exec, s[8:9]
	v_cvt_f32_u32_e32 v3, v0
	s_waitcnt vmcnt(0)
	v_readfirstlane_b32 s6, v2
	s_add_u32 s8, s30, 0x3500
	s_addc_u32 s9, s31, 0
	v_rcp_iflag_f32_e32 v3, v3
	v_add_u32_e32 v1, s6, v1
	v_add_u32_e32 v4, 1, v1
	s_mov_b64 s[10:11], -1
	v_mul_f32_e32 v2, 0x4f7ffffe, v3
	v_cvt_u32_f32_e32 v2, v2
	v_sub_u32_e32 v3, 0, v0
	v_mul_lo_u32 v3, v3, v2
	v_mul_hi_u32 v3, v2, v3
	v_add_u32_e32 v2, v2, v3
	v_mul_hi_u32 v2, v1, v2
	v_mul_lo_u32 v3, v2, v0
	v_sub_u32_e32 v1, v1, v3
	v_add_u32_e32 v5, 1, v2
	v_cmp_ge_u32_e32 vcc, v1, v0
	v_sub_u32_e32 v3, v1, v0
	s_nop 0
	v_cndmask_b32_e32 v2, v2, v5, vcc
	v_cndmask_b32_e32 v1, v1, v3, vcc
	v_add_u32_e32 v3, 1, v2
	v_cmp_ge_u32_e32 vcc, v1, v0
	s_nop 1
	v_cndmask_b32_e32 v2, v2, v3, vcc
	v_mul_lo_u32 v1, v0, v2
	v_add_u32_e32 v0, v1, v0
	v_cmp_ne_u32_e32 vcc, v4, v0
	v_mov_b64_e32 v[0:1], s[8:9]
	s_and_saveexec_b64 s[6:7], vcc
	s_cbranch_execz .LBB0_418
	v_mov_b32_e32 v1, 0x23fe4
	ds_read_b32 v1, v1
	v_add_u32_e32 v2, 1, v2
	s_waitcnt lgkmcnt(0)
	v_mul_lo_u32 v2, v2, v1
	v_mov_b32_e32 v0, 0
	global_load_dword v1, v0, s[8:9] offset:-256 sc1
	s_mov_b64 s[14:15], 0
	s_waitcnt vmcnt(0)
	v_cmp_lt_u32_e32 vcc, v1, v2
	s_and_saveexec_b64 s[12:13], vcc
	s_cbranch_execz .LBB0_417
	s_add_u32 s10, s30, 0x200
	s_addc_u32 s11, s31, 0
	s_mov_b32 s16, 1
	s_branch .LBB0_410

; __device__ __forceinline__ unsigned xb_ld(unsigned* p)              { return __hip_atomic_load(p, __ATOMIC_RELAXED, __HIP_MEMORY_SCOPE_AGENT); }
; #define XB_SPIN(cond, bar) do { unsigned _sp = 0; while (cond) { __builtin_amdgcn_s_sleep(1); \
;     if ((++_sp & 255u) == 0u) { if (xb_ld(&(bar)[XB_TMO])) break; if (_sp > XB_SPIN_CAP) { atomicAdd(&(bar)[XB_TMO], 1u); break; } } } } while (0)
; __device__ __forceinline__ void xcd_barrier(const XcdBarrier& b) {
;     ...
;             else XB_SPIN(xb_ld(&bar[XB_TOPGEN]) == tg, bar);
.LBB0_412:
	global_load_dword v1, v0, s[8:9] offset:-256 sc1
	s_add_i32 s16, s16, 1
	s_mov_b64 s[62:63], -1
	s_waitcnt vmcnt(0)
	v_cmp_ge_u32_e32 vcc, v1, v2
	s_orn2_b64 s[68:69], vcc, exec
	s_branch .LBB0_409

; __device__ __forceinline__ unsigned xb_add(unsigned* p, unsigned v) { return __hip_atomic_fetch_add(p, v, __ATOMIC_RELAXED, __HIP_MEMORY_SCOPE_AGENT); }
; __device__ __forceinline__ void xcd_barrier(const XcdBarrier& b) {
;     ...
;             __builtin_amdgcn_fence(__ATOMIC_ACQUIRE, "agent");
;             xb_add(&bar[XB_XGEN(b.x)], 1u);
;             asm volatile("s_waitcnt vmcnt(0)" ::: "memory");
.LBB0_420:
	s_or_b64 exec, exec, s[6:7]
	s_mov_b64 s[6:7], exec
	v_mbcnt_lo_u32_b32 v0, s6, 0
	v_mbcnt_hi_u32_b32 v0, s7, v0
	v_cmp_eq_u32_e32 vcc, 0, v0
	s_waitcnt vmcnt(0)
	buffer_inv sc1
	s_and_saveexec_b64 s[8:9], vcc
	s_cbranch_execz .LBB0_422
	s_bcnt1_i32_b64 s6, s[6:7]
	v_mov_b32_e32 v0, 0x2000
	v_mov_b32_e32 v1, s6
.LBB0_422:
	s_or_b64 exec, exec, s[8:9]
	s_waitcnt vmcnt(0)

; __device__ __forceinline__ unsigned xb_ld(unsigned* p)              { return __hip_atomic_load(p, __ATOMIC_RELAXED, __HIP_MEMORY_SCOPE_AGENT); }
; __device__ __forceinline__ unsigned xb_add(unsigned* p, unsigned v) { return __hip_atomic_fetch_add(p, v, __ATOMIC_RELAXED, __HIP_MEMORY_SCOPE_AGENT); }
; #define XB_SPIN(cond, bar) do { unsigned _sp = 0; while (cond) { __builtin_amdgcn_s_sleep(1); \
;     if ((++_sp & 255u) == 0u) { if (xb_ld(&(bar)[XB_TMO])) break; if (_sp > XB_SPIN_CAP) { atomicAdd(&(bar)[XB_TMO], 1u); break; } } } } while (0)
; __device__ __forceinline__ void xcd_barrier(const XcdBarrier& b) {
;     ...
;         const unsigned old = xb_add(&bar[XB_XSUB(b.x)], 1u);
;         const unsigned gen = old / nloc;
;         if (old + 1u == (gen + 1u) * nloc) {
;             __builtin_amdgcn_fence(__ATOMIC_RELEASE, "agent");
;             asm volatile("s_waitcnt vmcnt(0)" ::: "memory");
;             const unsigned og = xb_add(&bar[XB_TOP], 1u);
;             const unsigned tg = og / nx;
;             if (og + 1u == (tg + 1u) * nx) xb_add(&bar[XB_TOPGEN], 1u);
;             else XB_SPIN(xb_ld(&bar[XB_TOPGEN]) == tg, bar);
;             __builtin_amdgcn_fence(__ATOMIC_ACQUIRE, "agent");
;             xb_add(&bar[XB_XGEN(b.x)], 1u);
;             asm volatile("s_waitcnt vmcnt(0)" ::: "memory");
;         } else {
;             XB_SPIN(xb_ld(&bar[XB_XGEN(b.x)]) == gen, bar);
.LBB0_502:
	s_or_b64 exec, exec, s[8:9]
	v_cvt_f32_u32_e32 v4, v2
	s_waitcnt vmcnt(0)
	v_readfirstlane_b32 s6, v3
	v_sub_u32_e32 v3, 0, v2
	v_rcp_iflag_f32_e32 v4, v4
	v_add_u32_e32 v5, s6, v1
	v_mul_f32_e32 v4, 0x4f7ffffe, v4
	v_cvt_u32_f32_e32 v4, v4
	v_mul_lo_u32 v1, v3, v4
	v_mul_hi_u32 v1, v4, v1
	v_add_u32_e32 v1, v4, v1
	v_mul_hi_u32 v1, v5, v1
	v_mul_lo_u32 v3, v1, v2
	v_sub_u32_e32 v3, v5, v3
	v_add_u32_e32 v4, 1, v1
	v_cmp_ge_u32_e32 vcc, v3, v2
	s_nop 1
	v_cndmask_b32_e32 v1, v1, v4, vcc
	v_sub_u32_e32 v4, v3, v2
	v_cndmask_b32_e32 v3, v3, v4, vcc
	v_add_u32_e32 v4, 1, v1
	v_cmp_ge_u32_e32 vcc, v3, v2
	v_add_u32_e32 v3, 1, v5
	s_nop 0
	v_cndmask_b32_e32 v1, v1, v4, vcc
	v_mul_lo_u32 v4, v2, v1
	v_add_u32_e32 v2, v4, v2
	v_cmp_ne_u32_e32 vcc, v3, v2
	s_and_saveexec_b64 s[6:7], vcc
	s_xor_b64 s[6:7], exec, s[6:7]
	s_cbranch_execz .LBB0_516
	s_waitcnt lgkmcnt(0)
	v_mov_b32_e32 v0, 0x23fe4
	ds_read_b32 v0, v0
	v_add_u32_e32 v1, 1, v1
	s_waitcnt lgkmcnt(0)
	v_mul_lo_u32 v1, v1, v0
	v_mov_b32_e32 v0, 0x3400
	global_load_dword v0, v0, s[30:31] sc1
	s_add_u32 s12, s30, 0x3400
	s_addc_u32 s13, s31, 0
	s_waitcnt vmcnt(0)
	v_cmp_lt_u32_e32 vcc, v0, v1
	s_and_saveexec_b64 s[8:9], vcc
	s_cbranch_execz .LBB0_515
	s_mov_b32 s16, 1
	s_mov_b64 s[14:15], 0
	v_mov_b32_e32 v0, 0
	s_branch .LBB0_506

; __device__ __forceinline__ unsigned xb_ld(unsigned* p)              { return __hip_atomic_load(p, __ATOMIC_RELAXED, __HIP_MEMORY_SCOPE_AGENT); }
; #define XB_SPIN(cond, bar) do { unsigned _sp = 0; while (cond) { __builtin_amdgcn_s_sleep(1); \
;     if ((++_sp & 255u) == 0u) { if (xb_ld(&(bar)[XB_TMO])) break; if (_sp > XB_SPIN_CAP) { atomicAdd(&(bar)[XB_TMO], 1u); break; } } } } while (0)
; __device__ __forceinline__ void xcd_barrier(const XcdBarrier& b) {
;     ...
;             XB_SPIN(xb_ld(&bar[XB_XGEN(b.x)]) == gen, bar);
.LBB0_508:
	global_load_dword v2, v0, s[12:13] sc1
	s_add_i32 s16, s16, 1
	s_mov_b64 s[70:71], -1
	s_waitcnt vmcnt(0)
	v_cmp_ge_u32_e32 vcc, v2, v1
	s_orn2_b64 s[68:69], vcc, exec
	s_branch .LBB0_505

; __device__ __forceinline__ unsigned xb_ld(unsigned* p)              { return __hip_atomic_load(p, __ATOMIC_RELAXED, __HIP_MEMORY_SCOPE_AGENT); }
; __device__ __forceinline__ unsigned xb_add(unsigned* p, unsigned v) { return __hip_atomic_fetch_add(p, v, __ATOMIC_RELAXED, __HIP_MEMORY_SCOPE_AGENT); }
; #define XB_SPIN(cond, bar) do { unsigned _sp = 0; while (cond) { __builtin_amdgcn_s_sleep(1); \
;     if ((++_sp & 255u) == 0u) { if (xb_ld(&(bar)[XB_TMO])) break; if (_sp > XB_SPIN_CAP) { atomicAdd(&(bar)[XB_TMO], 1u); break; } } } } while (0)
; __device__ __forceinline__ void xcd_barrier(const XcdBarrier& b) {
;     ...
;             const unsigned og = xb_add(&bar[XB_TOP], 1u);
;             const unsigned tg = og / nx;
;             if (og + 1u == (tg + 1u) * nx) xb_add(&bar[XB_TOPGEN], 1u);
;             else XB_SPIN(xb_ld(&bar[XB_TOPGEN]) == tg, bar);
.LBB0_519:
	s_or_b64 exec, exec, s[8:9]
	v_cvt_f32_u32_e32 v3, v0
	s_waitcnt vmcnt(0)
	v_readfirstlane_b32 s6, v2
	s_add_u32 s8, s30, 0x3500
	s_addc_u32 s9, s31, 0
	v_rcp_iflag_f32_e32 v3, v3
	v_add_u32_e32 v1, s6, v1
	v_add_u32_e32 v4, 1, v1
	s_mov_b64 s[12:13], -1
	v_mul_f32_e32 v2, 0x4f7ffffe, v3
	v_cvt_u32_f32_e32 v2, v2
	v_sub_u32_e32 v3, 0, v0
	v_mul_lo_u32 v3, v3, v2
	v_mul_hi_u32 v3, v2, v3
	v_add_u32_e32 v2, v2, v3
	v_mul_hi_u32 v2, v1, v2
	v_mul_lo_u32 v3, v2, v0
	v_sub_u32_e32 v1, v1, v3
	v_add_u32_e32 v5, 1, v2
	v_cmp_ge_u32_e32 vcc, v1, v0
	v_sub_u32_e32 v3, v1, v0
	s_nop 0
	v_cndmask_b32_e32 v2, v2, v5, vcc
	v_cndmask_b32_e32 v1, v1, v3, vcc
	v_add_u32_e32 v3, 1, v2
	v_cmp_ge_u32_e32 vcc, v1, v0
	s_nop 1
	v_cndmask_b32_e32 v2, v2, v3, vcc
	v_mul_lo_u32 v1, v0, v2
	v_add_u32_e32 v0, v1, v0
	v_cmp_ne_u32_e32 vcc, v4, v0
	v_mov_b64_e32 v[0:1], s[8:9]
	s_and_saveexec_b64 s[6:7], vcc
	s_cbranch_execz .LBB0_531
	v_mov_b32_e32 v1, 0x23fe4
	ds_read_b32 v1, v1
	v_add_u32_e32 v2, 1, v2
	s_waitcnt lgkmcnt(0)
	v_mul_lo_u32 v2, v2, v1
	v_mov_b32_e32 v0, 0
	global_load_dword v1, v0, s[8:9] offset:-256 sc1
	s_mov_b64 s[64:65], 0
	s_waitcnt vmcnt(0)
	v_cmp_lt_u32_e32 vcc, v1, v2
	s_and_saveexec_b64 s[14:15], vcc
	s_cbranch_execz .LBB0_530
	s_add_u32 s12, s30, 0x200
	s_addc_u32 s13, s31, 0
	s_mov_b32 s16, 1
	s_branch .LBB0_523

; __device__ __forceinline__ unsigned xb_ld(unsigned* p)              { return __hip_atomic_load(p, __ATOMIC_RELAXED, __HIP_MEMORY_SCOPE_AGENT); }
; #define XB_SPIN(cond, bar) do { unsigned _sp = 0; while (cond) { __builtin_amdgcn_s_sleep(1); \
;     if ((++_sp & 255u) == 0u) { if (xb_ld(&(bar)[XB_TMO])) break; if (_sp > XB_SPIN_CAP) { atomicAdd(&(bar)[XB_TMO], 1u); break; } } } } while (0)
; __device__ __forceinline__ void xcd_barrier(const XcdBarrier& b) {
;     ...
;             else XB_SPIN(xb_ld(&bar[XB_TOPGEN]) == tg, bar);
.LBB0_525:
	global_load_dword v1, v0, s[8:9] offset:-256 sc1
	s_add_i32 s16, s16, 1
	s_mov_b64 s[70:71], -1
	s_waitcnt vmcnt(0)
	v_cmp_ge_u32_e32 vcc, v1, v2
	s_orn2_b64 s[74:75], vcc, exec
	s_branch .LBB0_522

; __device__ __forceinline__ unsigned xb_add(unsigned* p, unsigned v) { return __hip_atomic_fetch_add(p, v, __ATOMIC_RELAXED, __HIP_MEMORY_SCOPE_AGENT); }
; __device__ __forceinline__ void xcd_barrier(const XcdBarrier& b) {
;     ...
;             __builtin_amdgcn_fence(__ATOMIC_ACQUIRE, "agent");
;             xb_add(&bar[XB_XGEN(b.x)], 1u);
;             asm volatile("s_waitcnt vmcnt(0)" ::: "memory");
.LBB0_533:
	s_or_b64 exec, exec, s[6:7]
	s_mov_b64 s[6:7], exec
	v_mbcnt_lo_u32_b32 v0, s6, 0
	v_mbcnt_hi_u32_b32 v0, s7, v0
	v_cmp_eq_u32_e32 vcc, 0, v0
	s_waitcnt vmcnt(0)
	buffer_inv sc1
	s_and_saveexec_b64 s[8:9], vcc
	s_cbranch_execz .LBB0_535
	s_bcnt1_i32_b64 s6, s[6:7]
	v_mov_b32_e32 v0, 0x2000
	v_mov_b32_e32 v1, s6
.LBB0_535:
	s_or_b64 exec, exec, s[8:9]
	s_waitcnt vmcnt(0)

; __device__ __forceinline__ unsigned xb_ld(unsigned* p)              { return __hip_atomic_load(p, __ATOMIC_RELAXED, __HIP_MEMORY_SCOPE_AGENT); }
; #define XB_SPIN(cond, bar) do { unsigned _sp = 0; while (cond) { __builtin_amdgcn_s_sleep(1); \
;     if ((++_sp & 255u) == 0u) { if (xb_ld(&(bar)[XB_TMO])) break; if (_sp > XB_SPIN_CAP) { atomicAdd(&(bar)[XB_TMO], 1u); break; } } } } while (0)
; __device__ __forceinline__ void xcd_barrier(const XcdBarrier& b) {
;     ...
;             XB_SPIN(xb_ld(&bar[XB_XGEN(b.x)]) == gen, bar);
.LBB0_658:
	global_load_dword v2, v0, s[10:11] sc1
	s_add_i32 s16, s16, 1
	s_mov_b64 s[68:69], -1
	s_waitcnt vmcnt(0)
	v_cmp_ge_u32_e32 vcc, v2, v1
	s_orn2_b64 s[64:65], vcc, exec
	s_branch .LBB0_655

; __device__ __forceinline__ unsigned xb_ld(unsigned* p)              { return __hip_atomic_load(p, __ATOMIC_RELAXED, __HIP_MEMORY_SCOPE_AGENT); }
; #define XB_SPIN(cond, bar) do { unsigned _sp = 0; while (cond) { __builtin_amdgcn_s_sleep(1); \
;     if ((++_sp & 255u) == 0u) { if (xb_ld(&(bar)[XB_TMO])) break; if (_sp > XB_SPIN_CAP) { atomicAdd(&(bar)[XB_TMO], 1u); break; } } } } while (0)
; __device__ __forceinline__ void xcd_barrier(const XcdBarrier& b) {
;     ...
;             else XB_SPIN(xb_ld(&bar[XB_TOPGEN]) == tg, bar);
.LBB0_675:
	global_load_dword v1, v0, s[8:9] offset:-256 sc1
	s_add_i32 s16, s16, 1
	s_mov_b64 s[68:69], -1
	s_waitcnt vmcnt(0)
	v_cmp_ge_u32_e32 vcc, v1, v2
	s_orn2_b64 s[72:73], vcc, exec
	s_branch .LBB0_672

; __device__ __forceinline__ unsigned xb_add(unsigned* p, unsigned v) { return __hip_atomic_fetch_add(p, v, __ATOMIC_RELAXED, __HIP_MEMORY_SCOPE_AGENT); }
; __device__ __forceinline__ void xcd_barrier(const XcdBarrier& b) {
;     ...
;             __builtin_amdgcn_fence(__ATOMIC_ACQUIRE, "agent");
;             xb_add(&bar[XB_XGEN(b.x)], 1u);
;             asm volatile("s_waitcnt vmcnt(0)" ::: "memory");
.LBB0_683:
	s_or_b64 exec, exec, s[6:7]
	s_mov_b64 s[6:7], exec
	v_mbcnt_lo_u32_b32 v0, s6, 0
	v_mbcnt_hi_u32_b32 v0, s7, v0
	v_cmp_eq_u32_e32 vcc, 0, v0
	s_waitcnt vmcnt(0)
	buffer_inv sc1
	s_and_saveexec_b64 s[8:9], vcc
	s_cbranch_execz .LBB0_685
	s_bcnt1_i32_b64 s6, s[6:7]
	v_mov_b32_e32 v0, 0x2000
	v_mov_b32_e32 v1, s6
.LBB0_685:
	s_or_b64 exec, exec, s[8:9]
	s_waitcnt vmcnt(0)

; __device__ __forceinline__ unsigned xb_ld(unsigned* p)              { return __hip_atomic_load(p, __ATOMIC_RELAXED, __HIP_MEMORY_SCOPE_AGENT); }
; __device__ __forceinline__ unsigned xb_add(unsigned* p, unsigned v) { return __hip_atomic_fetch_add(p, v, __ATOMIC_RELAXED, __HIP_MEMORY_SCOPE_AGENT); }
; #define XB_SPIN(cond, bar) do { unsigned _sp = 0; while (cond) { __builtin_amdgcn_s_sleep(1); \
;     if ((++_sp & 255u) == 0u) { if (xb_ld(&(bar)[XB_TMO])) break; if (_sp > XB_SPIN_CAP) { atomicAdd(&(bar)[XB_TMO], 1u); break; } } } } while (0)
; __device__ __forceinline__ void xcd_barrier(const XcdBarrier& b) {
;     ...
;         const unsigned old = xb_add(&bar[XB_XSUB(b.x)], 1u);
;         const unsigned gen = old / nloc;
;         if (old + 1u == (gen + 1u) * nloc) {
;             __builtin_amdgcn_fence(__ATOMIC_RELEASE, "agent");
;             asm volatile("s_waitcnt vmcnt(0)" ::: "memory");
;             const unsigned og = xb_add(&bar[XB_TOP], 1u);
;             const unsigned tg = og / nx;
;             if (og + 1u == (tg + 1u) * nx) xb_add(&bar[XB_TOPGEN], 1u);
;             else XB_SPIN(xb_ld(&bar[XB_TOPGEN]) == tg, bar);
;             __builtin_amdgcn_fence(__ATOMIC_ACQUIRE, "agent");
;             xb_add(&bar[XB_XGEN(b.x)], 1u);
;             asm volatile("s_waitcnt vmcnt(0)" ::: "memory");
;         } else {
;             XB_SPIN(xb_ld(&bar[XB_XGEN(b.x)]) == gen, bar);
.LBB0_763:
	s_or_b64 exec, exec, s[8:9]
	v_cvt_f32_u32_e32 v4, v2
	s_waitcnt vmcnt(0)
	v_readfirstlane_b32 s2, v3
	v_sub_u32_e32 v3, 0, v2
	v_rcp_iflag_f32_e32 v4, v4
	v_add_u32_e32 v5, s2, v1
	v_mul_f32_e32 v4, 0x4f7ffffe, v4
	v_cvt_u32_f32_e32 v4, v4
	v_mul_lo_u32 v1, v3, v4
	v_mul_hi_u32 v1, v4, v1
	v_add_u32_e32 v1, v4, v1
	v_mul_hi_u32 v1, v5, v1
	v_mul_lo_u32 v3, v1, v2
	v_sub_u32_e32 v3, v5, v3
	v_add_u32_e32 v4, 1, v1
	v_cmp_ge_u32_e32 vcc, v3, v2
	s_nop 1
	v_cndmask_b32_e32 v1, v1, v4, vcc
	v_sub_u32_e32 v4, v3, v2
	v_cndmask_b32_e32 v3, v3, v4, vcc
	v_add_u32_e32 v4, 1, v1
	v_cmp_ge_u32_e32 vcc, v3, v2
	v_add_u32_e32 v3, 1, v5
	s_nop 0
	v_cndmask_b32_e32 v1, v1, v4, vcc
	v_mul_lo_u32 v4, v2, v1
	v_add_u32_e32 v2, v4, v2
	v_cmp_ne_u32_e32 vcc, v3, v2
	s_and_saveexec_b64 s[6:7], vcc
	s_xor_b64 s[6:7], exec, s[6:7]
	s_cbranch_execz .LBB0_777
	s_waitcnt lgkmcnt(0)
	v_mov_b32_e32 v0, 0x23fe4
	ds_read_b32 v0, v0
	v_add_u32_e32 v1, 1, v1
	s_waitcnt lgkmcnt(0)
	v_mul_lo_u32 v1, v1, v0
	v_mov_b32_e32 v0, 0x3400
	global_load_dword v0, v0, s[30:31] sc1
	s_add_u32 s10, s30, 0x3400
	s_addc_u32 s11, s31, 0
	s_waitcnt vmcnt(0)
	v_cmp_lt_u32_e32 vcc, v0, v1
	s_and_saveexec_b64 s[8:9], vcc
	s_cbranch_execz .LBB0_776
	s_mov_b32 s2, 1
	s_mov_b64 s[12:13], 0
	v_mov_b32_e32 v0, 0
	s_branch .LBB0_767

; __device__ __forceinline__ unsigned xb_ld(unsigned* p)              { return __hip_atomic_load(p, __ATOMIC_RELAXED, __HIP_MEMORY_SCOPE_AGENT); }
; #define XB_SPIN(cond, bar) do { unsigned _sp = 0; while (cond) { __builtin_amdgcn_s_sleep(1); \
;     if ((++_sp & 255u) == 0u) { if (xb_ld(&(bar)[XB_TMO])) break; if (_sp > XB_SPIN_CAP) { atomicAdd(&(bar)[XB_TMO], 1u); break; } } } } while (0)
; __device__ __forceinline__ void xcd_barrier(const XcdBarrier& b) {
;     ...
;             XB_SPIN(xb_ld(&bar[XB_XGEN(b.x)]) == gen, bar);
.LBB0_769:
	global_load_dword v2, v0, s[10:11] sc1
	s_add_i32 s2, s2, 1
	s_mov_b64 s[54:55], -1
	s_waitcnt vmcnt(0)
	v_cmp_ge_u32_e32 vcc, v2, v1
	s_orn2_b64 s[52:53], vcc, exec
	s_branch .LBB0_766

; __device__ __forceinline__ unsigned xb_ld(unsigned* p)              { return __hip_atomic_load(p, __ATOMIC_RELAXED, __HIP_MEMORY_SCOPE_AGENT); }
; __device__ __forceinline__ unsigned xb_add(unsigned* p, unsigned v) { return __hip_atomic_fetch_add(p, v, __ATOMIC_RELAXED, __HIP_MEMORY_SCOPE_AGENT); }
; #define XB_SPIN(cond, bar) do { unsigned _sp = 0; while (cond) { __builtin_amdgcn_s_sleep(1); \
;     if ((++_sp & 255u) == 0u) { if (xb_ld(&(bar)[XB_TMO])) break; if (_sp > XB_SPIN_CAP) { atomicAdd(&(bar)[XB_TMO], 1u); break; } } } } while (0)
; __device__ __forceinline__ void xcd_barrier(const XcdBarrier& b) {
;     ...
;             const unsigned og = xb_add(&bar[XB_TOP], 1u);
;             const unsigned tg = og / nx;
;             if (og + 1u == (tg + 1u) * nx) xb_add(&bar[XB_TOPGEN], 1u);
;             else XB_SPIN(xb_ld(&bar[XB_TOPGEN]) == tg, bar);
.LBB0_780:
	s_or_b64 exec, exec, s[8:9]
	v_cvt_f32_u32_e32 v3, v0
	s_waitcnt vmcnt(0)
	v_readfirstlane_b32 s2, v2
	s_add_u32 s8, s30, 0x3500
	s_addc_u32 s9, s31, 0
	v_rcp_iflag_f32_e32 v3, v3
	v_add_u32_e32 v1, s2, v1
	v_add_u32_e32 v4, 1, v1
	s_mov_b64 s[10:11], -1
	v_mul_f32_e32 v2, 0x4f7ffffe, v3
	v_cvt_u32_f32_e32 v2, v2
	v_sub_u32_e32 v3, 0, v0
	v_mul_lo_u32 v3, v3, v2
	v_mul_hi_u32 v3, v2, v3
	v_add_u32_e32 v2, v2, v3
	v_mul_hi_u32 v2, v1, v2
	v_mul_lo_u32 v3, v2, v0
	v_sub_u32_e32 v1, v1, v3
	v_add_u32_e32 v5, 1, v2
	v_cmp_ge_u32_e32 vcc, v1, v0
	v_sub_u32_e32 v3, v1, v0
	s_nop 0
	v_cndmask_b32_e32 v2, v2, v5, vcc
	v_cndmask_b32_e32 v1, v1, v3, vcc
	v_add_u32_e32 v3, 1, v2
	v_cmp_ge_u32_e32 vcc, v1, v0
	s_nop 1
	v_cndmask_b32_e32 v2, v2, v3, vcc
	v_mul_lo_u32 v1, v0, v2
	v_add_u32_e32 v0, v1, v0
	v_cmp_ne_u32_e32 vcc, v4, v0
	v_mov_b64_e32 v[0:1], s[8:9]
	s_and_saveexec_b64 s[6:7], vcc
	s_cbranch_execz .LBB0_792
	v_mov_b32_e32 v1, 0x23fe4
	ds_read_b32 v1, v1
	v_add_u32_e32 v2, 1, v2
	s_waitcnt lgkmcnt(0)
	v_mul_lo_u32 v2, v2, v1
	v_mov_b32_e32 v0, 0
	global_load_dword v1, v0, s[8:9] offset:-256 sc1
	s_mov_b64 s[14:15], 0
	s_waitcnt vmcnt(0)
	v_cmp_lt_u32_e32 vcc, v1, v2
	s_and_saveexec_b64 s[12:13], vcc
	s_cbranch_execz .LBB0_791
	s_add_u32 s10, s30, 0x200
	s_addc_u32 s11, s31, 0
	s_mov_b32 s2, 1
	s_branch .LBB0_784

; __device__ __forceinline__ unsigned xb_ld(unsigned* p)              { return __hip_atomic_load(p, __ATOMIC_RELAXED, __HIP_MEMORY_SCOPE_AGENT); }
; #define XB_SPIN(cond, bar) do { unsigned _sp = 0; while (cond) { __builtin_amdgcn_s_sleep(1); \
;     if ((++_sp & 255u) == 0u) { if (xb_ld(&(bar)[XB_TMO])) break; if (_sp > XB_SPIN_CAP) { atomicAdd(&(bar)[XB_TMO], 1u); break; } } } } while (0)
; __device__ __forceinline__ void xcd_barrier(const XcdBarrier& b) {
;     ...
;             else XB_SPIN(xb_ld(&bar[XB_TOPGEN]) == tg, bar);
.LBB0_786:
	global_load_dword v1, v0, s[8:9] offset:-256 sc1
	s_add_i32 s2, s2, 1
	s_mov_b64 s[54:55], -1
	s_waitcnt vmcnt(0)
	v_cmp_ge_u32_e32 vcc, v1, v2
	s_orn2_b64 s[62:63], vcc, exec
	s_branch .LBB0_783

; __device__ __forceinline__ unsigned xb_add(unsigned* p, unsigned v) { return __hip_atomic_fetch_add(p, v, __ATOMIC_RELAXED, __HIP_MEMORY_SCOPE_AGENT); }
; __device__ __forceinline__ void xcd_barrier(const XcdBarrier& b) {
;     ...
;             __builtin_amdgcn_fence(__ATOMIC_ACQUIRE, "agent");
;             xb_add(&bar[XB_XGEN(b.x)], 1u);
;             asm volatile("s_waitcnt vmcnt(0)" ::: "memory");
.LBB0_794:
	s_or_b64 exec, exec, s[6:7]
	s_mov_b64 s[6:7], exec
	v_mbcnt_lo_u32_b32 v0, s6, 0
	v_mbcnt_hi_u32_b32 v0, s7, v0
	v_cmp_eq_u32_e32 vcc, 0, v0
	s_waitcnt vmcnt(0)
	buffer_inv sc1
	s_and_saveexec_b64 s[8:9], vcc
	s_cbranch_execz .LBB0_796
	s_bcnt1_i32_b64 s2, s[6:7]
	v_mov_b32_e32 v0, 0x2000
	v_mov_b32_e32 v1, s2
.LBB0_796:
	s_or_b64 exec, exec, s[8:9]
	s_waitcnt vmcnt(0)

; __device__ __forceinline__ unsigned xb_ld(unsigned* p)              { return __hip_atomic_load(p, __ATOMIC_RELAXED, __HIP_MEMORY_SCOPE_AGENT); }
; __device__ __forceinline__ unsigned xb_add(unsigned* p, unsigned v) { return __hip_atomic_fetch_add(p, v, __ATOMIC_RELAXED, __HIP_MEMORY_SCOPE_AGENT); }
; #define XB_SPIN(cond, bar) do { unsigned _sp = 0; while (cond) { __builtin_amdgcn_s_sleep(1); \
;     if ((++_sp & 255u) == 0u) { if (xb_ld(&(bar)[XB_TMO])) break; if (_sp > XB_SPIN_CAP) { atomicAdd(&(bar)[XB_TMO], 1u); break; } } } } while (0)
; __device__ __forceinline__ void xcd_barrier(const XcdBarrier& b) {
;     ...
;         const unsigned old = xb_add(&bar[XB_XSUB(b.x)], 1u);
;         const unsigned gen = old / nloc;
;         if (old + 1u == (gen + 1u) * nloc) {
;             __builtin_amdgcn_fence(__ATOMIC_RELEASE, "agent");
;             asm volatile("s_waitcnt vmcnt(0)" ::: "memory");
;             const unsigned og = xb_add(&bar[XB_TOP], 1u);
;             const unsigned tg = og / nx;
;             if (og + 1u == (tg + 1u) * nx) xb_add(&bar[XB_TOPGEN], 1u);
;             else XB_SPIN(xb_ld(&bar[XB_TOPGEN]) == tg, bar);
;             __builtin_amdgcn_fence(__ATOMIC_ACQUIRE, "agent");
;             xb_add(&bar[XB_XGEN(b.x)], 1u);
;             asm volatile("s_waitcnt vmcnt(0)" ::: "memory");
;         } else {
;             XB_SPIN(xb_ld(&bar[XB_XGEN(b.x)]) == gen, bar);
.LBB0_897:
	s_or_b64 exec, exec, s[10:11]
	v_cvt_f32_u32_e32 v4, v2
	s_waitcnt vmcnt(0)
	v_readfirstlane_b32 s2, v3
	v_sub_u32_e32 v3, 0, v2
	v_rcp_iflag_f32_e32 v4, v4
	v_add_u32_e32 v5, s2, v1
	v_mul_f32_e32 v4, 0x4f7ffffe, v4
	v_cvt_u32_f32_e32 v4, v4
	v_mul_lo_u32 v1, v3, v4
	v_mul_hi_u32 v1, v4, v1
	v_add_u32_e32 v1, v4, v1
	v_mul_hi_u32 v1, v5, v1
	v_mul_lo_u32 v3, v1, v2
	v_sub_u32_e32 v3, v5, v3
	v_add_u32_e32 v4, 1, v1
	v_cmp_ge_u32_e32 vcc, v3, v2
	s_nop 1
	v_cndmask_b32_e32 v1, v1, v4, vcc
	v_sub_u32_e32 v4, v3, v2
	v_cndmask_b32_e32 v3, v3, v4, vcc
	v_add_u32_e32 v4, 1, v1
	v_cmp_ge_u32_e32 vcc, v3, v2
	v_add_u32_e32 v3, 1, v5
	s_nop 0
	v_cndmask_b32_e32 v1, v1, v4, vcc
	v_mul_lo_u32 v4, v2, v1
	v_add_u32_e32 v2, v4, v2
	v_cmp_ne_u32_e32 vcc, v3, v2
	s_and_saveexec_b64 s[6:7], vcc
	s_xor_b64 s[6:7], exec, s[6:7]
	s_cbranch_execz .LBB0_911
	s_waitcnt lgkmcnt(0)
	v_mov_b32_e32 v0, 0x23fe4
	ds_read_b32 v0, v0
	v_add_u32_e32 v1, 1, v1
	s_waitcnt lgkmcnt(0)
	v_mul_lo_u32 v1, v1, v0
	v_mov_b32_e32 v0, 0x3400
	global_load_dword v0, v0, s[30:31] sc1
	s_add_u32 s12, s30, 0x3400
	s_addc_u32 s13, s31, 0
	s_waitcnt vmcnt(0)
	v_cmp_lt_u32_e32 vcc, v0, v1
	s_and_saveexec_b64 s[10:11], vcc
	s_cbranch_execz .LBB0_910
	s_mov_b32 s2, 1
	s_mov_b64 s[14:15], 0
	v_mov_b32_e32 v0, 0
	s_branch .LBB0_901

; __device__ __forceinline__ unsigned xb_ld(unsigned* p)              { return __hip_atomic_load(p, __ATOMIC_RELAXED, __HIP_MEMORY_SCOPE_AGENT); }
; #define XB_SPIN(cond, bar) do { unsigned _sp = 0; while (cond) { __builtin_amdgcn_s_sleep(1); \
;     if ((++_sp & 255u) == 0u) { if (xb_ld(&(bar)[XB_TMO])) break; if (_sp > XB_SPIN_CAP) { atomicAdd(&(bar)[XB_TMO], 1u); break; } } } } while (0)
; __device__ __forceinline__ void xcd_barrier(const XcdBarrier& b) {
;     ...
;             XB_SPIN(xb_ld(&bar[XB_XGEN(b.x)]) == gen, bar);
.LBB0_903:
	global_load_dword v2, v0, s[12:13] sc1
	s_add_i32 s2, s2, 1
	s_mov_b64 s[56:57], -1
	s_waitcnt vmcnt(0)
	v_cmp_ge_u32_e32 vcc, v2, v1
	s_orn2_b64 s[54:55], vcc, exec
	s_branch .LBB0_900

; __device__ __forceinline__ unsigned xb_ld(unsigned* p)              { return __hip_atomic_load(p, __ATOMIC_RELAXED, __HIP_MEMORY_SCOPE_AGENT); }
; __device__ __forceinline__ unsigned xb_add(unsigned* p, unsigned v) { return __hip_atomic_fetch_add(p, v, __ATOMIC_RELAXED, __HIP_MEMORY_SCOPE_AGENT); }
; #define XB_SPIN(cond, bar) do { unsigned _sp = 0; while (cond) { __builtin_amdgcn_s_sleep(1); \
;     if ((++_sp & 255u) == 0u) { if (xb_ld(&(bar)[XB_TMO])) break; if (_sp > XB_SPIN_CAP) { atomicAdd(&(bar)[XB_TMO], 1u); break; } } } } while (0)
; __device__ __forceinline__ void xcd_barrier(const XcdBarrier& b) {
;     ...
;             const unsigned og = xb_add(&bar[XB_TOP], 1u);
;             const unsigned tg = og / nx;
;             if (og + 1u == (tg + 1u) * nx) xb_add(&bar[XB_TOPGEN], 1u);
;             else XB_SPIN(xb_ld(&bar[XB_TOPGEN]) == tg, bar);
.LBB0_914:
	s_or_b64 exec, exec, s[10:11]
	v_cvt_f32_u32_e32 v3, v0
	s_waitcnt vmcnt(0)
	v_readfirstlane_b32 s2, v2
	s_add_u32 s10, s30, 0x3500
	s_addc_u32 s11, s31, 0
	v_rcp_iflag_f32_e32 v3, v3
	v_add_u32_e32 v1, s2, v1
	v_add_u32_e32 v4, 1, v1
	s_mov_b64 s[12:13], -1
	v_mul_f32_e32 v2, 0x4f7ffffe, v3
	v_cvt_u32_f32_e32 v2, v2
	v_sub_u32_e32 v3, 0, v0
	v_mul_lo_u32 v3, v3, v2
	v_mul_hi_u32 v3, v2, v3
	v_add_u32_e32 v2, v2, v3
	v_mul_hi_u32 v2, v1, v2
	v_mul_lo_u32 v3, v2, v0
	v_sub_u32_e32 v1, v1, v3
	v_add_u32_e32 v5, 1, v2
	v_cmp_ge_u32_e32 vcc, v1, v0
	v_sub_u32_e32 v3, v1, v0
	s_nop 0
	v_cndmask_b32_e32 v2, v2, v5, vcc
	v_cndmask_b32_e32 v1, v1, v3, vcc
	v_add_u32_e32 v3, 1, v2
	v_cmp_ge_u32_e32 vcc, v1, v0
	s_nop 1
	v_cndmask_b32_e32 v2, v2, v3, vcc
	v_mul_lo_u32 v1, v0, v2
	v_add_u32_e32 v0, v1, v0
	v_cmp_ne_u32_e32 vcc, v4, v0
	v_mov_b64_e32 v[0:1], s[10:11]
	s_and_saveexec_b64 s[6:7], vcc
	s_cbranch_execz .LBB0_926
	v_mov_b32_e32 v1, 0x23fe4
	ds_read_b32 v1, v1
	v_add_u32_e32 v2, 1, v2
	s_waitcnt lgkmcnt(0)
	v_mul_lo_u32 v2, v2, v1
	v_mov_b32_e32 v0, 0
	global_load_dword v1, v0, s[10:11] offset:-256 sc1
	s_mov_b64 s[52:53], 0
	s_waitcnt vmcnt(0)
	v_cmp_lt_u32_e32 vcc, v1, v2
	s_and_saveexec_b64 s[14:15], vcc
	s_cbranch_execz .LBB0_925
	s_add_u32 s12, s30, 0x200
	s_addc_u32 s13, s31, 0
	s_mov_b32 s2, 1
	s_branch .LBB0_918

; __device__ __forceinline__ unsigned xb_ld(unsigned* p)              { return __hip_atomic_load(p, __ATOMIC_RELAXED, __HIP_MEMORY_SCOPE_AGENT); }
; #define XB_SPIN(cond, bar) do { unsigned _sp = 0; while (cond) { __builtin_amdgcn_s_sleep(1); \
;     if ((++_sp & 255u) == 0u) { if (xb_ld(&(bar)[XB_TMO])) break; if (_sp > XB_SPIN_CAP) { atomicAdd(&(bar)[XB_TMO], 1u); break; } } } } while (0)
; __device__ __forceinline__ void xcd_barrier(const XcdBarrier& b) {
;     ...
;             else XB_SPIN(xb_ld(&bar[XB_TOPGEN]) == tg, bar);
.LBB0_920:
	global_load_dword v1, v0, s[10:11] offset:-256 sc1
	s_add_i32 s2, s2, 1
	s_mov_b64 s[56:57], -1
	s_waitcnt vmcnt(0)
	v_cmp_ge_u32_e32 vcc, v1, v2
	s_orn2_b64 s[64:65], vcc, exec
	s_branch .LBB0_917

; __device__ __forceinline__ unsigned xb_add(unsigned* p, unsigned v) { return __hip_atomic_fetch_add(p, v, __ATOMIC_RELAXED, __HIP_MEMORY_SCOPE_AGENT); }
; __device__ __forceinline__ void xcd_barrier(const XcdBarrier& b) {
;     ...
;             __builtin_amdgcn_fence(__ATOMIC_ACQUIRE, "agent");
;             xb_add(&bar[XB_XGEN(b.x)], 1u);
;             asm volatile("s_waitcnt vmcnt(0)" ::: "memory");
.LBB0_928:
	s_or_b64 exec, exec, s[6:7]
	s_mov_b64 s[6:7], exec
	v_mbcnt_lo_u32_b32 v0, s6, 0
	v_mbcnt_hi_u32_b32 v0, s7, v0
	v_cmp_eq_u32_e32 vcc, 0, v0
	s_waitcnt vmcnt(0)
	buffer_inv sc1
	s_and_saveexec_b64 s[10:11], vcc
	s_cbranch_execz .LBB0_930
	s_bcnt1_i32_b64 s2, s[6:7]
	v_mov_b32_e32 v0, 0x2000
	v_mov_b32_e32 v1, s2
.LBB0_930:
	s_or_b64 exec, exec, s[10:11]
	s_waitcnt vmcnt(0)

; __device__ __forceinline__ unsigned xb_ld(unsigned* p)              { return __hip_atomic_load(p, __ATOMIC_RELAXED, __HIP_MEMORY_SCOPE_AGENT); }
; #define XB_SPIN(cond, bar) do { unsigned _sp = 0; while (cond) { __builtin_amdgcn_s_sleep(1); \
;     if ((++_sp & 255u) == 0u) { if (xb_ld(&(bar)[XB_TMO])) break; if (_sp > XB_SPIN_CAP) { atomicAdd(&(bar)[XB_TMO], 1u); break; } } } } while (0)
; __device__ __forceinline__ void xcd_barrier(const XcdBarrier& b) {
;     ...
;             else XB_SPIN(xb_ld(&bar[XB_TOPGEN]) == tg, bar);
.LBB0_984:
	global_load_dword v1, v0, s[10:11] offset:-256 sc1
	s_add_i32 s2, s2, 1
	s_mov_b64 s[56:57], -1
	s_waitcnt vmcnt(0)
	v_cmp_ge_u32_e32 vcc, v1, v2
	s_orn2_b64 s[62:63], vcc, exec
	s_branch .LBB0_981

; __device__ __forceinline__ unsigned xb_add(unsigned* p, unsigned v) { return __hip_atomic_fetch_add(p, v, __ATOMIC_RELAXED, __HIP_MEMORY_SCOPE_AGENT); }
; __device__ __forceinline__ void xcd_barrier(const XcdBarrier& b) {
;     ...
;             __builtin_amdgcn_fence(__ATOMIC_ACQUIRE, "agent");
;             xb_add(&bar[XB_XGEN(b.x)], 1u);
;             asm volatile("s_waitcnt vmcnt(0)" ::: "memory");
.LBB0_992:
	s_or_b64 exec, exec, s[6:7]
	s_mov_b64 s[6:7], exec
	v_mbcnt_lo_u32_b32 v0, s6, 0
	v_mbcnt_hi_u32_b32 v0, s7, v0
	v_cmp_eq_u32_e32 vcc, 0, v0
	s_waitcnt vmcnt(0)
	buffer_inv sc1
	s_and_saveexec_b64 s[10:11], vcc
	s_cbranch_execz .LBB0_994
	s_bcnt1_i32_b64 s2, s[6:7]
	v_mov_b32_e32 v0, 0x2000
	v_mov_b32_e32 v1, s2
.LBB0_994:
	s_or_b64 exec, exec, s[10:11]
	s_waitcnt vmcnt(0)

; __device__ __forceinline__ unsigned xb_ld(unsigned* p)              { return __hip_atomic_load(p, __ATOMIC_RELAXED, __HIP_MEMORY_SCOPE_AGENT); }
; __device__ __forceinline__ unsigned xb_add(unsigned* p, unsigned v) { return __hip_atomic_fetch_add(p, v, __ATOMIC_RELAXED, __HIP_MEMORY_SCOPE_AGENT); }
; #define XB_SPIN(cond, bar) do { unsigned _sp = 0; while (cond) { __builtin_amdgcn_s_sleep(1); \
;     if ((++_sp & 255u) == 0u) { if (xb_ld(&(bar)[XB_TMO])) break; if (_sp > XB_SPIN_CAP) { atomicAdd(&(bar)[XB_TMO], 1u); break; } } } } while (0)
; __device__ __forceinline__ void xcd_barrier(const XcdBarrier& b) {
;     ...
;         const unsigned old = xb_add(&bar[XB_XSUB(b.x)], 1u);
;         const unsigned gen = old / nloc;
;         if (old + 1u == (gen + 1u) * nloc) {
;             __builtin_amdgcn_fence(__ATOMIC_RELEASE, "agent");
;             asm volatile("s_waitcnt vmcnt(0)" ::: "memory");
;             const unsigned og = xb_add(&bar[XB_TOP], 1u);
;             const unsigned tg = og / nx;
;             if (og + 1u == (tg + 1u) * nx) xb_add(&bar[XB_TOPGEN], 1u);
;             else XB_SPIN(xb_ld(&bar[XB_TOPGEN]) == tg, bar);
;             __builtin_amdgcn_fence(__ATOMIC_ACQUIRE, "agent");
;             xb_add(&bar[XB_XGEN(b.x)], 1u);
;             asm volatile("s_waitcnt vmcnt(0)" ::: "memory");
;         } else {
;             XB_SPIN(xb_ld(&bar[XB_XGEN(b.x)]) == gen, bar);
.LBB0_1062:
	s_or_b64 exec, exec, s[10:11]
	v_cvt_f32_u32_e32 v4, v2
	s_waitcnt vmcnt(0)
	v_readfirstlane_b32 s2, v3
	v_sub_u32_e32 v3, 0, v2
	v_rcp_iflag_f32_e32 v4, v4
	v_add_u32_e32 v5, s2, v1
	v_mul_f32_e32 v4, 0x4f7ffffe, v4
	v_cvt_u32_f32_e32 v4, v4
	v_mul_lo_u32 v1, v3, v4
	v_mul_hi_u32 v1, v4, v1
	v_add_u32_e32 v1, v4, v1
	v_mul_hi_u32 v1, v5, v1
	v_mul_lo_u32 v3, v1, v2
	v_sub_u32_e32 v3, v5, v3
	v_add_u32_e32 v4, 1, v1
	v_cmp_ge_u32_e32 vcc, v3, v2
	s_nop 1
	v_cndmask_b32_e32 v1, v1, v4, vcc
	v_sub_u32_e32 v4, v3, v2
	v_cndmask_b32_e32 v3, v3, v4, vcc
	v_add_u32_e32 v4, 1, v1
	v_cmp_ge_u32_e32 vcc, v3, v2
	v_add_u32_e32 v3, 1, v5
	s_nop 0
	v_cndmask_b32_e32 v1, v1, v4, vcc
	v_mul_lo_u32 v4, v2, v1
	v_add_u32_e32 v2, v4, v2
	v_cmp_ne_u32_e32 vcc, v3, v2
	s_and_saveexec_b64 s[8:9], vcc
	s_xor_b64 s[8:9], exec, s[8:9]
	s_cbranch_execz .LBB0_1076
	s_waitcnt lgkmcnt(0)
	v_mov_b32_e32 v0, 0x23fe4
	ds_read_b32 v0, v0
	v_add_u32_e32 v1, 1, v1
	s_waitcnt lgkmcnt(0)
	v_mul_lo_u32 v1, v1, v0
	v_mov_b32_e32 v0, 0x3400
	global_load_dword v0, v0, s[30:31] sc1
	s_add_u32 s12, s30, 0x3400
	s_addc_u32 s13, s31, 0
	s_waitcnt vmcnt(0)
	v_cmp_lt_u32_e32 vcc, v0, v1
	s_and_saveexec_b64 s[10:11], vcc
	s_cbranch_execz .LBB0_1075
	s_mov_b32 s2, 1
	s_mov_b64 s[14:15], 0
	v_mov_b32_e32 v0, 0
	s_branch .LBB0_1066

; __device__ __forceinline__ unsigned xb_ld(unsigned* p)              { return __hip_atomic_load(p, __ATOMIC_RELAXED, __HIP_MEMORY_SCOPE_AGENT); }
; #define XB_SPIN(cond, bar) do { unsigned _sp = 0; while (cond) { __builtin_amdgcn_s_sleep(1); \
;     if ((++_sp & 255u) == 0u) { if (xb_ld(&(bar)[XB_TMO])) break; if (_sp > XB_SPIN_CAP) { atomicAdd(&(bar)[XB_TMO], 1u); break; } } } } while (0)
; __device__ __forceinline__ void xcd_barrier(const XcdBarrier& b) {
;     ...
;             XB_SPIN(xb_ld(&bar[XB_XGEN(b.x)]) == gen, bar);
.LBB0_1068:
	global_load_dword v2, v0, s[12:13] sc1
	s_add_i32 s2, s2, 1
	s_mov_b64 s[54:55], -1
	s_waitcnt vmcnt(0)
	v_cmp_ge_u32_e32 vcc, v2, v1
	s_orn2_b64 s[52:53], vcc, exec
	s_branch .LBB0_1065

; __device__ __forceinline__ unsigned xb_ld(unsigned* p)              { return __hip_atomic_load(p, __ATOMIC_RELAXED, __HIP_MEMORY_SCOPE_AGENT); }
; __device__ __forceinline__ unsigned xb_add(unsigned* p, unsigned v) { return __hip_atomic_fetch_add(p, v, __ATOMIC_RELAXED, __HIP_MEMORY_SCOPE_AGENT); }
; #define XB_SPIN(cond, bar) do { unsigned _sp = 0; while (cond) { __builtin_amdgcn_s_sleep(1); \
;     if ((++_sp & 255u) == 0u) { if (xb_ld(&(bar)[XB_TMO])) break; if (_sp > XB_SPIN_CAP) { atomicAdd(&(bar)[XB_TMO], 1u); break; } } } } while (0)
; __device__ __forceinline__ void xcd_barrier(const XcdBarrier& b) {
;     ...
;             const unsigned og = xb_add(&bar[XB_TOP], 1u);
;             const unsigned tg = og / nx;
;             if (og + 1u == (tg + 1u) * nx) xb_add(&bar[XB_TOPGEN], 1u);
;             else XB_SPIN(xb_ld(&bar[XB_TOPGEN]) == tg, bar);
.LBB0_1079:
	s_or_b64 exec, exec, s[10:11]
	v_cvt_f32_u32_e32 v3, v0
	s_waitcnt vmcnt(0)
	v_readfirstlane_b32 s2, v2
	s_add_u32 s10, s30, 0x3500
	s_addc_u32 s11, s31, 0
	v_rcp_iflag_f32_e32 v3, v3
	v_add_u32_e32 v1, s2, v1
	v_add_u32_e32 v4, 1, v1
	s_mov_b64 s[12:13], -1
	v_mul_f32_e32 v2, 0x4f7ffffe, v3
	v_cvt_u32_f32_e32 v2, v2
	v_sub_u32_e32 v3, 0, v0
	v_mul_lo_u32 v3, v3, v2
	v_mul_hi_u32 v3, v2, v3
	v_add_u32_e32 v2, v2, v3
	v_mul_hi_u32 v2, v1, v2
	v_mul_lo_u32 v3, v2, v0
	v_sub_u32_e32 v1, v1, v3
	v_add_u32_e32 v5, 1, v2
	v_cmp_ge_u32_e32 vcc, v1, v0
	v_sub_u32_e32 v3, v1, v0
	s_nop 0
	v_cndmask_b32_e32 v2, v2, v5, vcc
	v_cndmask_b32_e32 v1, v1, v3, vcc
	v_add_u32_e32 v3, 1, v2
	v_cmp_ge_u32_e32 vcc, v1, v0
	s_nop 1
	v_cndmask_b32_e32 v2, v2, v3, vcc
	v_mul_lo_u32 v1, v0, v2
	v_add_u32_e32 v0, v1, v0
	v_cmp_ne_u32_e32 vcc, v4, v0
	v_mov_b64_e32 v[0:1], s[10:11]
	s_and_saveexec_b64 s[8:9], vcc
	s_cbranch_execz .LBB0_1091
	v_mov_b32_e32 v1, 0x23fe4
	ds_read_b32 v1, v1
	v_add_u32_e32 v2, 1, v2
	s_waitcnt lgkmcnt(0)
	v_mul_lo_u32 v2, v2, v1
	v_mov_b32_e32 v0, 0
	global_load_dword v1, v0, s[10:11] offset:-256 sc1
	s_mov_b64 s[44:45], 0
	s_waitcnt vmcnt(0)
	v_cmp_lt_u32_e32 vcc, v1, v2
	s_and_saveexec_b64 s[14:15], vcc
	s_cbranch_execz .LBB0_1090
	s_add_u32 s12, s30, 0x200
	s_addc_u32 s13, s31, 0
	s_mov_b32 s2, 1
	s_branch .LBB0_1083

; __device__ __forceinline__ unsigned xb_ld(unsigned* p)              { return __hip_atomic_load(p, __ATOMIC_RELAXED, __HIP_MEMORY_SCOPE_AGENT); }
; #define XB_SPIN(cond, bar) do { unsigned _sp = 0; while (cond) { __builtin_amdgcn_s_sleep(1); \
;     if ((++_sp & 255u) == 0u) { if (xb_ld(&(bar)[XB_TMO])) break; if (_sp > XB_SPIN_CAP) { atomicAdd(&(bar)[XB_TMO], 1u); break; } } } } while (0)
; __device__ __forceinline__ void xcd_barrier(const XcdBarrier& b) {
;     ...
;             else XB_SPIN(xb_ld(&bar[XB_TOPGEN]) == tg, bar);
.LBB0_1085:
	global_load_dword v1, v0, s[10:11] offset:-256 sc1
	s_add_i32 s2, s2, 1
	s_mov_b64 s[54:55], -1
	s_waitcnt vmcnt(0)
	v_cmp_ge_u32_e32 vcc, v1, v2
	s_orn2_b64 s[58:59], vcc, exec
	s_branch .LBB0_1082

; __device__ __forceinline__ unsigned xb_add(unsigned* p, unsigned v) { return __hip_atomic_fetch_add(p, v, __ATOMIC_RELAXED, __HIP_MEMORY_SCOPE_AGENT); }
; __device__ __forceinline__ void xcd_barrier(const XcdBarrier& b) {
;     ...
;             __builtin_amdgcn_fence(__ATOMIC_ACQUIRE, "agent");
;             xb_add(&bar[XB_XGEN(b.x)], 1u);
;             asm volatile("s_waitcnt vmcnt(0)" ::: "memory");
.LBB0_1093:
	s_or_b64 exec, exec, s[8:9]
	s_mov_b64 s[8:9], exec
	v_mbcnt_lo_u32_b32 v0, s8, 0
	v_mbcnt_hi_u32_b32 v0, s9, v0
	v_cmp_eq_u32_e32 vcc, 0, v0
	s_waitcnt vmcnt(0)
	buffer_inv sc1
	s_and_saveexec_b64 s[10:11], vcc
	s_cbranch_execz .LBB0_1095
	s_bcnt1_i32_b64 s2, s[8:9]
	v_mov_b32_e32 v0, 0x2000
	v_mov_b32_e32 v1, s2
.LBB0_1095:
	s_or_b64 exec, exec, s[10:11]
	s_waitcnt vmcnt(0)

; __device__ __forceinline__ unsigned xb_ld(unsigned* p)              { return __hip_atomic_load(p, __ATOMIC_RELAXED, __HIP_MEMORY_SCOPE_AGENT); }
; #define XB_SPIN(cond, bar) do { unsigned _sp = 0; while (cond) { __builtin_amdgcn_s_sleep(1); \
;     if ((++_sp & 255u) == 0u) { if (xb_ld(&(bar)[XB_TMO])) break; if (_sp > XB_SPIN_CAP) { atomicAdd(&(bar)[XB_TMO], 1u); break; } } } } while (0)
; __device__ __forceinline__ void xcd_barrier(const XcdBarrier& b) {
;     ...
;             XB_SPIN(xb_ld(&bar[XB_XGEN(b.x)]) == gen, bar);
.LBB0_1144:
	global_load_dword v2, v0, s[12:13] sc1
	s_add_i32 s2, s2, 1
	s_mov_b64 s[44:45], -1
	s_waitcnt vmcnt(0)
	v_cmp_ge_u32_e32 vcc, v2, v1
	s_orn2_b64 s[42:43], vcc, exec
	s_branch .LBB0_1141

; __device__ __forceinline__ unsigned xb_ld(unsigned* p)              { return __hip_atomic_load(p, __ATOMIC_RELAXED, __HIP_MEMORY_SCOPE_AGENT); }
; __device__ __forceinline__ unsigned xb_add(unsigned* p, unsigned v) { return __hip_atomic_fetch_add(p, v, __ATOMIC_RELAXED, __HIP_MEMORY_SCOPE_AGENT); }
; #define XB_SPIN(cond, bar) do { unsigned _sp = 0; while (cond) { __builtin_amdgcn_s_sleep(1); \
;     if ((++_sp & 255u) == 0u) { if (xb_ld(&(bar)[XB_TMO])) break; if (_sp > XB_SPIN_CAP) { atomicAdd(&(bar)[XB_TMO], 1u); break; } } } } while (0)
; __device__ __forceinline__ void xcd_barrier(const XcdBarrier& b) {
;     ...
;             const unsigned og = xb_add(&bar[XB_TOP], 1u);
;             const unsigned tg = og / nx;
;             if (og + 1u == (tg + 1u) * nx) xb_add(&bar[XB_TOPGEN], 1u);
;             else XB_SPIN(xb_ld(&bar[XB_TOPGEN]) == tg, bar);
.LBB0_1155:
	s_or_b64 exec, exec, s[10:11]
	v_cvt_f32_u32_e32 v3, v0
	s_waitcnt vmcnt(0)
	v_readfirstlane_b32 s2, v2
	s_add_u32 s10, s30, 0x3500
	s_addc_u32 s11, s31, 0
	v_rcp_iflag_f32_e32 v3, v3
	v_add_u32_e32 v1, s2, v1
	v_add_u32_e32 v4, 1, v1
	s_mov_b64 s[12:13], -1
	v_mul_f32_e32 v2, 0x4f7ffffe, v3
	v_cvt_u32_f32_e32 v2, v2
	v_sub_u32_e32 v3, 0, v0
	v_mul_lo_u32 v3, v3, v2
	v_mul_hi_u32 v3, v2, v3
	v_add_u32_e32 v2, v2, v3
	v_mul_hi_u32 v2, v1, v2
	v_mul_lo_u32 v3, v2, v0
	v_sub_u32_e32 v1, v1, v3
	v_add_u32_e32 v5, 1, v2
	v_cmp_ge_u32_e32 vcc, v1, v0
	v_sub_u32_e32 v3, v1, v0
	s_nop 0
	v_cndmask_b32_e32 v2, v2, v5, vcc
	v_cndmask_b32_e32 v1, v1, v3, vcc
	v_add_u32_e32 v3, 1, v2
	v_cmp_ge_u32_e32 vcc, v1, v0
	s_nop 1
	v_cndmask_b32_e32 v2, v2, v3, vcc
	v_mul_lo_u32 v1, v0, v2
	v_add_u32_e32 v0, v1, v0
	v_cmp_ne_u32_e32 vcc, v4, v0
	v_mov_b64_e32 v[0:1], s[10:11]
	s_and_saveexec_b64 s[8:9], vcc
	s_cbranch_execz .LBB0_1167
	v_mov_b32_e32 v1, 0x23fe4
	ds_read_b32 v1, v1
	v_add_u32_e32 v2, 1, v2
	s_waitcnt lgkmcnt(0)
	v_mul_lo_u32 v2, v2, v1
	v_mov_b32_e32 v0, 0
	global_load_dword v1, v0, s[10:11] offset:-256 sc1
	s_mov_b64 s[40:41], 0
	s_waitcnt vmcnt(0)
	v_cmp_lt_u32_e32 vcc, v1, v2
	s_and_saveexec_b64 s[14:15], vcc
	s_cbranch_execz .LBB0_1166
	s_add_u32 s12, s30, 0x200
	s_addc_u32 s13, s31, 0
	s_mov_b32 s2, 1
	s_branch .LBB0_1159

; __device__ __forceinline__ unsigned xb_ld(unsigned* p)              { return __hip_atomic_load(p, __ATOMIC_RELAXED, __HIP_MEMORY_SCOPE_AGENT); }
; #define XB_SPIN(cond, bar) do { unsigned _sp = 0; while (cond) { __builtin_amdgcn_s_sleep(1); \
;     if ((++_sp & 255u) == 0u) { if (xb_ld(&(bar)[XB_TMO])) break; if (_sp > XB_SPIN_CAP) { atomicAdd(&(bar)[XB_TMO], 1u); break; } } } } while (0)
; __device__ __forceinline__ void xcd_barrier(const XcdBarrier& b) {
;     ...
;             else XB_SPIN(xb_ld(&bar[XB_TOPGEN]) == tg, bar);
.LBB0_1161:
	global_load_dword v1, v0, s[10:11] offset:-256 sc1
	s_add_i32 s2, s2, 1
	s_mov_b64 s[44:45], -1
	s_waitcnt vmcnt(0)
	v_cmp_ge_u32_e32 vcc, v1, v2
	s_orn2_b64 s[54:55], vcc, exec
	s_branch .LBB0_1158

; __device__ __forceinline__ unsigned xb_add(unsigned* p, unsigned v) { return __hip_atomic_fetch_add(p, v, __ATOMIC_RELAXED, __HIP_MEMORY_SCOPE_AGENT); }
; __device__ __forceinline__ void xcd_barrier(const XcdBarrier& b) {
;     ...
;             __builtin_amdgcn_fence(__ATOMIC_ACQUIRE, "agent");
;             xb_add(&bar[XB_XGEN(b.x)], 1u);
;             asm volatile("s_waitcnt vmcnt(0)" ::: "memory");
.LBB0_1169:
	s_or_b64 exec, exec, s[8:9]
	s_mov_b64 s[8:9], exec
	v_mbcnt_lo_u32_b32 v0, s8, 0
	v_mbcnt_hi_u32_b32 v0, s9, v0
	v_cmp_eq_u32_e32 vcc, 0, v0
	s_waitcnt vmcnt(0)
	buffer_inv sc1
	s_and_saveexec_b64 s[10:11], vcc
	s_cbranch_execz .LBB0_1171
	s_bcnt1_i32_b64 s2, s[8:9]
	v_mov_b32_e32 v0, 0x2000
	v_mov_b32_e32 v1, s2
.LBB0_1171:
	s_or_b64 exec, exec, s[10:11]
	s_waitcnt vmcnt(0)

; __device__ __forceinline__ unsigned xb_ld(unsigned* p)              { return __hip_atomic_load(p, __ATOMIC_RELAXED, __HIP_MEMORY_SCOPE_AGENT); }
; __device__ __forceinline__ unsigned xb_add(unsigned* p, unsigned v) { return __hip_atomic_fetch_add(p, v, __ATOMIC_RELAXED, __HIP_MEMORY_SCOPE_AGENT); }
; #define XB_SPIN(cond, bar) do { unsigned _sp = 0; while (cond) { __builtin_amdgcn_s_sleep(1); \
;     if ((++_sp & 255u) == 0u) { if (xb_ld(&(bar)[XB_TMO])) break; if (_sp > XB_SPIN_CAP) { atomicAdd(&(bar)[XB_TMO], 1u); break; } } } } while (0)
; __device__ __forceinline__ void xcd_barrier(const XcdBarrier& b) {
;     ...
;         const unsigned old = xb_add(&bar[XB_XSUB(b.x)], 1u);
;         const unsigned gen = old / nloc;
;         if (old + 1u == (gen + 1u) * nloc) {
;             __builtin_amdgcn_fence(__ATOMIC_RELEASE, "agent");
;             asm volatile("s_waitcnt vmcnt(0)" ::: "memory");
;             const unsigned og = xb_add(&bar[XB_TOP], 1u);
;             const unsigned tg = og / nx;
;             if (og + 1u == (tg + 1u) * nx) xb_add(&bar[XB_TOPGEN], 1u);
;             else XB_SPIN(xb_ld(&bar[XB_TOPGEN]) == tg, bar);
;             __builtin_amdgcn_fence(__ATOMIC_ACQUIRE, "agent");
;             xb_add(&bar[XB_XGEN(b.x)], 1u);
;             asm volatile("s_waitcnt vmcnt(0)" ::: "memory");
;         } else {
;             XB_SPIN(xb_ld(&bar[XB_XGEN(b.x)]) == gen, bar);
.LBB0_1193:
	s_or_b64 exec, exec, s[12:13]
	v_cvt_f32_u32_e32 v4, v2
	s_waitcnt vmcnt(0)
	v_readfirstlane_b32 s2, v3
	v_sub_u32_e32 v3, 0, v2
	v_rcp_iflag_f32_e32 v4, v4
	v_add_u32_e32 v5, s2, v1
	v_mul_f32_e32 v4, 0x4f7ffffe, v4
	v_cvt_u32_f32_e32 v4, v4
	v_mul_lo_u32 v1, v3, v4
	v_mul_hi_u32 v1, v4, v1
	v_add_u32_e32 v1, v4, v1
	v_mul_hi_u32 v1, v5, v1
	v_mul_lo_u32 v3, v1, v2
	v_sub_u32_e32 v3, v5, v3
	v_add_u32_e32 v4, 1, v1
	v_cmp_ge_u32_e32 vcc, v3, v2
	s_nop 1
	v_cndmask_b32_e32 v1, v1, v4, vcc
	v_sub_u32_e32 v4, v3, v2
	v_cndmask_b32_e32 v3, v3, v4, vcc
	v_add_u32_e32 v4, 1, v1
	v_cmp_ge_u32_e32 vcc, v3, v2
	v_add_u32_e32 v3, 1, v5
	s_nop 0
	v_cndmask_b32_e32 v1, v1, v4, vcc
	v_mul_lo_u32 v4, v2, v1
	v_add_u32_e32 v2, v4, v2
	v_cmp_ne_u32_e32 vcc, v3, v2
	s_and_saveexec_b64 s[10:11], vcc
	s_xor_b64 s[10:11], exec, s[10:11]
	s_cbranch_execz .LBB0_1207
	s_waitcnt lgkmcnt(0)
	v_mov_b32_e32 v0, 0x23fe4
	ds_read_b32 v0, v0
	v_add_u32_e32 v1, 1, v1
	s_waitcnt lgkmcnt(0)
	v_mul_lo_u32 v1, v1, v0
	v_mov_b32_e32 v0, 0x3400
	global_load_dword v0, v0, s[30:31] sc1
	s_add_u32 s14, s30, 0x3400
	s_addc_u32 s15, s31, 0
	s_waitcnt vmcnt(0)
	v_cmp_lt_u32_e32 vcc, v0, v1
	s_and_saveexec_b64 s[12:13], vcc
	s_cbranch_execz .LBB0_1206
	s_mov_b32 s2, 1
	s_mov_b64 s[36:37], 0
	v_mov_b32_e32 v0, 0
	s_branch .LBB0_1197

; __device__ __forceinline__ unsigned xb_ld(unsigned* p)              { return __hip_atomic_load(p, __ATOMIC_RELAXED, __HIP_MEMORY_SCOPE_AGENT); }
; #define XB_SPIN(cond, bar) do { unsigned _sp = 0; while (cond) { __builtin_amdgcn_s_sleep(1); \
;     if ((++_sp & 255u) == 0u) { if (xb_ld(&(bar)[XB_TMO])) break; if (_sp > XB_SPIN_CAP) { atomicAdd(&(bar)[XB_TMO], 1u); break; } } } } while (0)
; __device__ __forceinline__ void xcd_barrier(const XcdBarrier& b) {
;     ...
;             XB_SPIN(xb_ld(&bar[XB_XGEN(b.x)]) == gen, bar);
.LBB0_1199:
	global_load_dword v2, v0, s[14:15] sc1
	s_add_i32 s2, s2, 1
	s_mov_b64 s[44:45], -1
	s_waitcnt vmcnt(0)
	v_cmp_ge_u32_e32 vcc, v2, v1
	s_orn2_b64 s[42:43], vcc, exec
	s_branch .LBB0_1196

; __device__ __forceinline__ unsigned xb_ld(unsigned* p)              { return __hip_atomic_load(p, __ATOMIC_RELAXED, __HIP_MEMORY_SCOPE_AGENT); }
; __device__ __forceinline__ unsigned xb_add(unsigned* p, unsigned v) { return __hip_atomic_fetch_add(p, v, __ATOMIC_RELAXED, __HIP_MEMORY_SCOPE_AGENT); }
; #define XB_SPIN(cond, bar) do { unsigned _sp = 0; while (cond) { __builtin_amdgcn_s_sleep(1); \
;     if ((++_sp & 255u) == 0u) { if (xb_ld(&(bar)[XB_TMO])) break; if (_sp > XB_SPIN_CAP) { atomicAdd(&(bar)[XB_TMO], 1u); break; } } } } while (0)
; __device__ __forceinline__ void xcd_barrier(const XcdBarrier& b) {
;     ...
;             const unsigned og = xb_add(&bar[XB_TOP], 1u);
;             const unsigned tg = og / nx;
;             if (og + 1u == (tg + 1u) * nx) xb_add(&bar[XB_TOPGEN], 1u);
;             else XB_SPIN(xb_ld(&bar[XB_TOPGEN]) == tg, bar);
.LBB0_1210:
	s_or_b64 exec, exec, s[12:13]
	v_cvt_f32_u32_e32 v3, v0
	s_waitcnt vmcnt(0)
	v_readfirstlane_b32 s2, v2
	s_add_u32 s12, s30, 0x3500
	s_addc_u32 s13, s31, 0
	v_rcp_iflag_f32_e32 v3, v3
	v_add_u32_e32 v1, s2, v1
	v_add_u32_e32 v4, 1, v1
	s_mov_b64 s[14:15], -1
	v_mul_f32_e32 v2, 0x4f7ffffe, v3
	v_cvt_u32_f32_e32 v2, v2
	v_sub_u32_e32 v3, 0, v0
	v_mul_lo_u32 v3, v3, v2
	v_mul_hi_u32 v3, v2, v3
	v_add_u32_e32 v2, v2, v3
	v_mul_hi_u32 v2, v1, v2
	v_mul_lo_u32 v3, v2, v0
	v_sub_u32_e32 v1, v1, v3
	v_add_u32_e32 v5, 1, v2
	v_cmp_ge_u32_e32 vcc, v1, v0
	v_sub_u32_e32 v3, v1, v0
	s_nop 0
	v_cndmask_b32_e32 v2, v2, v5, vcc
	v_cndmask_b32_e32 v1, v1, v3, vcc
	v_add_u32_e32 v3, 1, v2
	v_cmp_ge_u32_e32 vcc, v1, v0
	s_nop 1
	v_cndmask_b32_e32 v2, v2, v3, vcc
	v_mul_lo_u32 v1, v0, v2
	v_add_u32_e32 v0, v1, v0
	v_cmp_ne_u32_e32 vcc, v4, v0
	v_mov_b64_e32 v[0:1], s[12:13]
	s_and_saveexec_b64 s[10:11], vcc
	s_cbranch_execz .LBB0_1222
	v_mov_b32_e32 v1, 0x23fe4
	ds_read_b32 v1, v1
	v_add_u32_e32 v2, 1, v2
	s_waitcnt lgkmcnt(0)
	v_mul_lo_u32 v2, v2, v1
	v_mov_b32_e32 v0, 0
	global_load_dword v1, v0, s[12:13] offset:-256 sc1
	s_mov_b64 s[40:41], 0
	s_waitcnt vmcnt(0)
	v_cmp_lt_u32_e32 vcc, v1, v2
	s_and_saveexec_b64 s[36:37], vcc
	s_cbranch_execz .LBB0_1221
	s_add_u32 s14, s30, 0x200
	s_addc_u32 s15, s31, 0
	s_mov_b32 s2, 1
	s_branch .LBB0_1214

; __device__ __forceinline__ unsigned xb_ld(unsigned* p)              { return __hip_atomic_load(p, __ATOMIC_RELAXED, __HIP_MEMORY_SCOPE_AGENT); }
; #define XB_SPIN(cond, bar) do { unsigned _sp = 0; while (cond) { __builtin_amdgcn_s_sleep(1); \
;     if ((++_sp & 255u) == 0u) { if (xb_ld(&(bar)[XB_TMO])) break; if (_sp > XB_SPIN_CAP) { atomicAdd(&(bar)[XB_TMO], 1u); break; } } } } while (0)
; __device__ __forceinline__ void xcd_barrier(const XcdBarrier& b) {
;     ...
;             else XB_SPIN(xb_ld(&bar[XB_TOPGEN]) == tg, bar);
.LBB0_1216:
	global_load_dword v1, v0, s[12:13] offset:-256 sc1
	s_add_i32 s2, s2, 1
	s_mov_b64 s[44:45], -1
	s_waitcnt vmcnt(0)
	v_cmp_ge_u32_e32 vcc, v1, v2
	s_orn2_b64 s[50:51], vcc, exec
	s_branch .LBB0_1213

; __device__ __forceinline__ unsigned xb_add(unsigned* p, unsigned v) { return __hip_atomic_fetch_add(p, v, __ATOMIC_RELAXED, __HIP_MEMORY_SCOPE_AGENT); }
; __device__ __forceinline__ void xcd_barrier(const XcdBarrier& b) {
;     ...
;             __builtin_amdgcn_fence(__ATOMIC_ACQUIRE, "agent");
;             xb_add(&bar[XB_XGEN(b.x)], 1u);
;             asm volatile("s_waitcnt vmcnt(0)" ::: "memory");
.LBB0_1224:
	s_or_b64 exec, exec, s[10:11]
	s_mov_b64 s[10:11], exec
	v_mbcnt_lo_u32_b32 v0, s10, 0
	v_mbcnt_hi_u32_b32 v0, s11, v0
	v_cmp_eq_u32_e32 vcc, 0, v0
	s_waitcnt vmcnt(0)
	buffer_inv sc1
	s_and_saveexec_b64 s[12:13], vcc
	s_cbranch_execz .LBB0_1226
	s_bcnt1_i32_b64 s2, s[10:11]
	v_mov_b32_e32 v0, 0x2000
	v_mov_b32_e32 v1, s2
.LBB0_1226:
	s_or_b64 exec, exec, s[12:13]
	s_waitcnt vmcnt(0)

; __device__ __forceinline__ unsigned xb_ld(unsigned* p)              { return __hip_atomic_load(p, __ATOMIC_RELAXED, __HIP_MEMORY_SCOPE_AGENT); }
; __device__ __forceinline__ unsigned xb_add(unsigned* p, unsigned v) { return __hip_atomic_fetch_add(p, v, __ATOMIC_RELAXED, __HIP_MEMORY_SCOPE_AGENT); }
; #define XB_SPIN(cond, bar) do { unsigned _sp = 0; while (cond) { __builtin_amdgcn_s_sleep(1); \
;     if ((++_sp & 255u) == 0u) { if (xb_ld(&(bar)[XB_TMO])) break; if (_sp > XB_SPIN_CAP) { atomicAdd(&(bar)[XB_TMO], 1u); break; } } } } while (0)
; __device__ __forceinline__ void xcd_barrier(const XcdBarrier& b) {
;     ...
;         const unsigned old = xb_add(&bar[XB_XSUB(b.x)], 1u);
;         const unsigned gen = old / nloc;
;         if (old + 1u == (gen + 1u) * nloc) {
;             __builtin_amdgcn_fence(__ATOMIC_RELEASE, "agent");
;             asm volatile("s_waitcnt vmcnt(0)" ::: "memory");
;             const unsigned og = xb_add(&bar[XB_TOP], 1u);
;             const unsigned tg = og / nx;
;             if (og + 1u == (tg + 1u) * nx) xb_add(&bar[XB_TOPGEN], 1u);
;             else XB_SPIN(xb_ld(&bar[XB_TOPGEN]) == tg, bar);
;             __builtin_amdgcn_fence(__ATOMIC_ACQUIRE, "agent");
;             xb_add(&bar[XB_XGEN(b.x)], 1u);
;             asm volatile("s_waitcnt vmcnt(0)" ::: "memory");
;         } else {
;             XB_SPIN(xb_ld(&bar[XB_XGEN(b.x)]) == gen, bar);
.LBB0_1261:
	s_or_b64 exec, exec, s[12:13]
	v_cvt_f32_u32_e32 v4, v2
	s_waitcnt vmcnt(0)
	v_readfirstlane_b32 s2, v3
	v_sub_u32_e32 v3, 0, v2
	v_rcp_iflag_f32_e32 v4, v4
	v_add_u32_e32 v5, s2, v1
	v_mul_f32_e32 v4, 0x4f7ffffe, v4
	v_cvt_u32_f32_e32 v4, v4
	v_mul_lo_u32 v1, v3, v4
	v_mul_hi_u32 v1, v4, v1
	v_add_u32_e32 v1, v4, v1
	v_mul_hi_u32 v1, v5, v1
	v_mul_lo_u32 v3, v1, v2
	v_sub_u32_e32 v3, v5, v3
	v_add_u32_e32 v4, 1, v1
	v_cmp_ge_u32_e32 vcc, v3, v2
	s_nop 1
	v_cndmask_b32_e32 v1, v1, v4, vcc
	v_sub_u32_e32 v4, v3, v2
	v_cndmask_b32_e32 v3, v3, v4, vcc
	v_add_u32_e32 v4, 1, v1
	v_cmp_ge_u32_e32 vcc, v3, v2
	v_add_u32_e32 v3, 1, v5
	s_nop 0
	v_cndmask_b32_e32 v1, v1, v4, vcc
	v_mul_lo_u32 v4, v2, v1
	v_add_u32_e32 v2, v4, v2
	v_cmp_ne_u32_e32 vcc, v3, v2
	s_and_saveexec_b64 s[2:3], vcc
	s_xor_b64 s[10:11], exec, s[2:3]
	s_cbranch_execz .LBB0_1275
	s_waitcnt lgkmcnt(0)
	v_mov_b32_e32 v0, 0x23fe4
	ds_read_b32 v0, v0
	v_add_u32_e32 v1, 1, v1
	s_waitcnt lgkmcnt(0)
	v_mul_lo_u32 v1, v1, v0
	v_mov_b32_e32 v0, 0x3400
	global_load_dword v0, v0, s[30:31] sc1
	s_add_u32 s14, s30, 0x3400
	s_addc_u32 s15, s31, 0
	s_waitcnt vmcnt(0)
	v_cmp_lt_u32_e32 vcc, v0, v1
	s_and_saveexec_b64 s[12:13], vcc
	s_cbranch_execz .LBB0_1274
	s_mov_b32 s2, 1
	s_mov_b64 s[36:37], 0
	v_mov_b32_e32 v0, 0
	s_branch .LBB0_1265

; __device__ __forceinline__ unsigned xb_ld(unsigned* p)              { return __hip_atomic_load(p, __ATOMIC_RELAXED, __HIP_MEMORY_SCOPE_AGENT); }
; #define XB_SPIN(cond, bar) do { unsigned _sp = 0; while (cond) { __builtin_amdgcn_s_sleep(1); \
;     if ((++_sp & 255u) == 0u) { if (xb_ld(&(bar)[XB_TMO])) break; if (_sp > XB_SPIN_CAP) { atomicAdd(&(bar)[XB_TMO], 1u); break; } } } } while (0)
; __device__ __forceinline__ void xcd_barrier(const XcdBarrier& b) {
;     ...
;             XB_SPIN(xb_ld(&bar[XB_XGEN(b.x)]) == gen, bar);
.LBB0_1267:
	global_load_dword v2, v0, s[14:15] sc1
	s_add_i32 s2, s2, 1
	s_mov_b64 s[42:43], -1
	s_waitcnt vmcnt(0)
	v_cmp_ge_u32_e32 vcc, v2, v1
	s_orn2_b64 s[40:41], vcc, exec
	s_branch .LBB0_1264

; __device__ __forceinline__ unsigned xb_ld(unsigned* p)              { return __hip_atomic_load(p, __ATOMIC_RELAXED, __HIP_MEMORY_SCOPE_AGENT); }
; __device__ __forceinline__ unsigned xb_add(unsigned* p, unsigned v) { return __hip_atomic_fetch_add(p, v, __ATOMIC_RELAXED, __HIP_MEMORY_SCOPE_AGENT); }
; #define XB_SPIN(cond, bar) do { unsigned _sp = 0; while (cond) { __builtin_amdgcn_s_sleep(1); \
;     if ((++_sp & 255u) == 0u) { if (xb_ld(&(bar)[XB_TMO])) break; if (_sp > XB_SPIN_CAP) { atomicAdd(&(bar)[XB_TMO], 1u); break; } } } } while (0)
; __device__ __forceinline__ void xcd_barrier(const XcdBarrier& b) {
;     ...
;             const unsigned og = xb_add(&bar[XB_TOP], 1u);
;             const unsigned tg = og / nx;
;             if (og + 1u == (tg + 1u) * nx) xb_add(&bar[XB_TOPGEN], 1u);
;             else XB_SPIN(xb_ld(&bar[XB_TOPGEN]) == tg, bar);
.LBB0_1278:
	s_or_b64 exec, exec, s[12:13]
	v_cvt_f32_u32_e32 v3, v0
	s_waitcnt vmcnt(0)
	v_readfirstlane_b32 s2, v2
	s_add_u32 s12, s30, 0x3500
	s_addc_u32 s13, s31, 0
	v_rcp_iflag_f32_e32 v3, v3
	v_add_u32_e32 v1, s2, v1
	v_add_u32_e32 v4, 1, v1
	s_mov_b64 s[14:15], -1
	v_mul_f32_e32 v2, 0x4f7ffffe, v3
	v_cvt_u32_f32_e32 v2, v2
	v_sub_u32_e32 v3, 0, v0
	v_mul_lo_u32 v3, v3, v2
	v_mul_hi_u32 v3, v2, v3
	v_add_u32_e32 v2, v2, v3
	v_mul_hi_u32 v2, v1, v2
	v_mul_lo_u32 v3, v2, v0
	v_sub_u32_e32 v1, v1, v3
	v_add_u32_e32 v5, 1, v2
	v_cmp_ge_u32_e32 vcc, v1, v0
	v_sub_u32_e32 v3, v1, v0
	s_nop 0
	v_cndmask_b32_e32 v2, v2, v5, vcc
	v_cndmask_b32_e32 v1, v1, v3, vcc
	v_add_u32_e32 v3, 1, v2
	v_cmp_ge_u32_e32 vcc, v1, v0
	s_nop 1
	v_cndmask_b32_e32 v2, v2, v3, vcc
	v_mul_lo_u32 v1, v0, v2
	v_add_u32_e32 v0, v1, v0
	v_cmp_ne_u32_e32 vcc, v4, v0
	v_mov_b64_e32 v[0:1], s[12:13]
	s_and_saveexec_b64 s[10:11], vcc
	s_cbranch_execz .LBB0_1290
	v_mov_b32_e32 v1, 0x23fe4
	ds_read_b32 v1, v1
	v_add_u32_e32 v2, 1, v2
	s_waitcnt lgkmcnt(0)
	v_mul_lo_u32 v2, v2, v1
	v_mov_b32_e32 v0, 0
	global_load_dword v1, v0, s[12:13] offset:-256 sc1
	s_mov_b64 s[38:39], 0
	s_waitcnt vmcnt(0)
	v_cmp_lt_u32_e32 vcc, v1, v2
	s_and_saveexec_b64 s[36:37], vcc
	s_cbranch_execz .LBB0_1289
	s_add_u32 s14, s30, 0x200
	s_addc_u32 s15, s31, 0
	s_mov_b32 s2, 1
	s_branch .LBB0_1282

; __device__ __forceinline__ unsigned xb_ld(unsigned* p)              { return __hip_atomic_load(p, __ATOMIC_RELAXED, __HIP_MEMORY_SCOPE_AGENT); }
; #define XB_SPIN(cond, bar) do { unsigned _sp = 0; while (cond) { __builtin_amdgcn_s_sleep(1); \
;     if ((++_sp & 255u) == 0u) { if (xb_ld(&(bar)[XB_TMO])) break; if (_sp > XB_SPIN_CAP) { atomicAdd(&(bar)[XB_TMO], 1u); break; } } } } while (0)
; __device__ __forceinline__ void xcd_barrier(const XcdBarrier& b) {
;     ...
;             else XB_SPIN(xb_ld(&bar[XB_TOPGEN]) == tg, bar);
.LBB0_1284:
	global_load_dword v1, v0, s[12:13] offset:-256 sc1
	s_add_i32 s2, s2, 1
	s_mov_b64 s[42:43], -1
	s_waitcnt vmcnt(0)
	v_cmp_ge_u32_e32 vcc, v1, v2
	s_orn2_b64 s[46:47], vcc, exec
	s_branch .LBB0_1281

; __device__ __forceinline__ unsigned xb_add(unsigned* p, unsigned v) { return __hip_atomic_fetch_add(p, v, __ATOMIC_RELAXED, __HIP_MEMORY_SCOPE_AGENT); }
; __device__ __forceinline__ void xcd_barrier(const XcdBarrier& b) {
;     ...
;             __builtin_amdgcn_fence(__ATOMIC_ACQUIRE, "agent");
;             xb_add(&bar[XB_XGEN(b.x)], 1u);
;             asm volatile("s_waitcnt vmcnt(0)" ::: "memory");
.LBB0_1292:
	s_or_b64 exec, exec, s[10:11]
	s_mov_b64 s[10:11], exec
	v_mbcnt_lo_u32_b32 v0, s10, 0
	v_mbcnt_hi_u32_b32 v0, s11, v0
	v_cmp_eq_u32_e32 vcc, 0, v0
	s_waitcnt vmcnt(0)
	buffer_inv sc1
	s_and_saveexec_b64 s[12:13], vcc
	s_cbranch_execz .LBB0_1294
	s_bcnt1_i32_b64 s2, s[10:11]
	v_mov_b32_e32 v0, 0x2000
	v_mov_b32_e32 v1, s2
.LBB0_1294:
	s_or_b64 exec, exec, s[12:13]
	s_waitcnt vmcnt(0)

; __device__ __forceinline__ unsigned xb_ld(unsigned* p)              { return __hip_atomic_load(p, __ATOMIC_RELAXED, __HIP_MEMORY_SCOPE_AGENT); }
; __device__ __forceinline__ unsigned xb_add(unsigned* p, unsigned v) { return __hip_atomic_fetch_add(p, v, __ATOMIC_RELAXED, __HIP_MEMORY_SCOPE_AGENT); }
; #define XB_SPIN(cond, bar) do { unsigned _sp = 0; while (cond) { __builtin_amdgcn_s_sleep(1); \
;     if ((++_sp & 255u) == 0u) { if (xb_ld(&(bar)[XB_TMO])) break; if (_sp > XB_SPIN_CAP) { atomicAdd(&(bar)[XB_TMO], 1u); break; } } } } while (0)
; __device__ __forceinline__ void xcd_barrier(const XcdBarrier& b) {
;     ...
;         const unsigned old = xb_add(&bar[XB_XSUB(b.x)], 1u);
;         const unsigned gen = old / nloc;
;         if (old + 1u == (gen + 1u) * nloc) {
;             __builtin_amdgcn_fence(__ATOMIC_RELEASE, "agent");
;             asm volatile("s_waitcnt vmcnt(0)" ::: "memory");
;             const unsigned og = xb_add(&bar[XB_TOP], 1u);
;             const unsigned tg = og / nx;
;             if (og + 1u == (tg + 1u) * nx) xb_add(&bar[XB_TOPGEN], 1u);
;             else XB_SPIN(xb_ld(&bar[XB_TOPGEN]) == tg, bar);
.LBB0_1341:
	s_or_b64 exec, exec, s[8:9]
	v_cvt_f32_u32_e32 v4, v2
	s_waitcnt vmcnt(0)
	v_readfirstlane_b32 s6, v3
	v_sub_u32_e32 v3, 0, v2
	v_rcp_iflag_f32_e32 v4, v4
	v_add_u32_e32 v5, s6, v1
	v_mul_f32_e32 v4, 0x4f7ffffe, v4
	v_cvt_u32_f32_e32 v4, v4
	v_mul_lo_u32 v1, v3, v4
	v_mul_hi_u32 v1, v4, v1
	v_add_u32_e32 v1, v4, v1
	v_mul_hi_u32 v1, v5, v1
	v_mul_lo_u32 v3, v1, v2
	v_sub_u32_e32 v3, v5, v3
	v_add_u32_e32 v4, 1, v1
	v_cmp_ge_u32_e32 vcc, v3, v2
	s_nop 1
	v_cndmask_b32_e32 v1, v1, v4, vcc
	v_sub_u32_e32 v4, v3, v2
	v_cndmask_b32_e32 v3, v3, v4, vcc
	v_add_u32_e32 v4, 1, v1
	v_cmp_ge_u32_e32 vcc, v3, v2
	v_add_u32_e32 v3, 1, v5
	s_nop 0
	v_cndmask_b32_e32 v1, v1, v4, vcc
	v_mul_lo_u32 v4, v2, v1
	v_add_u32_e32 v2, v4, v2
	v_cmp_ne_u32_e32 vcc, v3, v2
	s_and_saveexec_b64 s[6:7], vcc
	s_xor_b64 s[6:7], exec, s[6:7]
	s_cbranch_execz .LBB0_1355
	s_waitcnt lgkmcnt(0)
	v_mov_b32_e32 v0, 0x23fe4
	ds_read_b32 v0, v0
	v_add_u32_e32 v1, 1, v1
	s_waitcnt lgkmcnt(0)
	v_mul_lo_u32 v1, v1, v0
	v_mov_b32_e32 v0, 0x3400
	global_load_dword v0, v0, s[30:31] sc1
	s_add_u32 s10, s30, 0x3400
	s_addc_u32 s11, s31, 0
	s_waitcnt vmcnt(0)
	v_cmp_lt_u32_e32 vcc, v0, v1
	s_and_saveexec_b64 s[8:9], vcc
	s_cbranch_execz .LBB0_1354
	s_mov_b32 s20, 1
	s_mov_b64 s[12:13], 0
	v_mov_b32_e32 v0, 0
	s_branch .LBB0_1345

; __device__ __forceinline__ unsigned xb_ld(unsigned* p)              { return __hip_atomic_load(p, __ATOMIC_RELAXED, __HIP_MEMORY_SCOPE_AGENT); }
; #define XB_SPIN(cond, bar) do { unsigned _sp = 0; while (cond) { __builtin_amdgcn_s_sleep(1); \
;     if ((++_sp & 255u) == 0u) { if (xb_ld(&(bar)[XB_TMO])) break; if (_sp > XB_SPIN_CAP) { atomicAdd(&(bar)[XB_TMO], 1u); break; } } } } while (0)
; __device__ __forceinline__ void xcd_barrier(const XcdBarrier& b) {
;     ...
;             else XB_SPIN(xb_ld(&bar[XB_TOPGEN]) == tg, bar);
.LBB0_1347:
	global_load_dword v2, v0, s[10:11] sc1
	s_add_i32 s20, s20, 1
	s_mov_b64 s[18:19], -1
	s_waitcnt vmcnt(0)
	v_cmp_ge_u32_e32 vcc, v2, v1
	s_orn2_b64 s[16:17], vcc, exec
	s_branch .LBB0_1344

; __device__ __forceinline__ unsigned xb_ld(unsigned* p)              { return __hip_atomic_load(p, __ATOMIC_RELAXED, __HIP_MEMORY_SCOPE_AGENT); }
; __device__ __forceinline__ unsigned xb_add(unsigned* p, unsigned v) { return __hip_atomic_fetch_add(p, v, __ATOMIC_RELAXED, __HIP_MEMORY_SCOPE_AGENT); }
; #define XB_SPIN(cond, bar) do { unsigned _sp = 0; while (cond) { __builtin_amdgcn_s_sleep(1); \
;     if ((++_sp & 255u) == 0u) { if (xb_ld(&(bar)[XB_TMO])) break; if (_sp > XB_SPIN_CAP) { atomicAdd(&(bar)[XB_TMO], 1u); break; } } } } while (0)
; __device__ __forceinline__ void xcd_barrier(const XcdBarrier& b) {
;     ...
;             const unsigned og = xb_add(&bar[XB_TOP], 1u);
;             const unsigned tg = og / nx;
;             if (og + 1u == (tg + 1u) * nx) xb_add(&bar[XB_TOPGEN], 1u);
;             else XB_SPIN(xb_ld(&bar[XB_TOPGEN]) == tg, bar);
.LBB0_1358:
	s_or_b64 exec, exec, s[8:9]
	v_cvt_f32_u32_e32 v3, v0
	s_waitcnt vmcnt(0)
	v_readfirstlane_b32 s6, v2
	s_add_u32 s8, s30, 0x3500
	s_addc_u32 s9, s31, 0
	v_rcp_iflag_f32_e32 v3, v3
	v_add_u32_e32 v1, s6, v1
	v_add_u32_e32 v4, 1, v1
	s_mov_b64 s[10:11], -1
	v_mul_f32_e32 v2, 0x4f7ffffe, v3
	v_cvt_u32_f32_e32 v2, v2
	v_sub_u32_e32 v3, 0, v0
	v_mul_lo_u32 v3, v3, v2
	v_mul_hi_u32 v3, v2, v3
	v_add_u32_e32 v2, v2, v3
	v_mul_hi_u32 v2, v1, v2
	v_mul_lo_u32 v3, v2, v0
	v_sub_u32_e32 v1, v1, v3
	v_add_u32_e32 v5, 1, v2
	v_cmp_ge_u32_e32 vcc, v1, v0
	v_sub_u32_e32 v3, v1, v0
	s_nop 0
	v_cndmask_b32_e32 v2, v2, v5, vcc
	v_cndmask_b32_e32 v1, v1, v3, vcc
	v_add_u32_e32 v3, 1, v2
	v_cmp_ge_u32_e32 vcc, v1, v0
	s_nop 1
	v_cndmask_b32_e32 v2, v2, v3, vcc
	v_mul_lo_u32 v1, v0, v2
	v_add_u32_e32 v0, v1, v0
	v_cmp_ne_u32_e32 vcc, v4, v0
	v_mov_b64_e32 v[0:1], s[8:9]
	s_and_saveexec_b64 s[6:7], vcc
	s_cbranch_execz .LBB0_1370
	v_mov_b32_e32 v1, 0x23fe4
	ds_read_b32 v1, v1
	v_add_u32_e32 v2, 1, v2
	s_waitcnt lgkmcnt(0)
	v_mul_lo_u32 v2, v2, v1
	v_mov_b32_e32 v0, 0
	global_load_dword v1, v0, s[8:9] offset:-256 sc1
	s_mov_b64 s[14:15], 0
	s_waitcnt vmcnt(0)
	v_cmp_lt_u32_e32 vcc, v1, v2
	s_and_saveexec_b64 s[12:13], vcc
	s_cbranch_execz .LBB0_1369
	s_add_u32 s10, s30, 0x200
	s_addc_u32 s11, s31, 0
	s_mov_b32 s20, 1
	s_branch .LBB0_1362

; __device__ __forceinline__ unsigned xb_ld(unsigned* p)              { return __hip_atomic_load(p, __ATOMIC_RELAXED, __HIP_MEMORY_SCOPE_AGENT); }
; #define XB_SPIN(cond, bar) do { unsigned _sp = 0; while (cond) { __builtin_amdgcn_s_sleep(1); \
;     if ((++_sp & 255u) == 0u) { if (xb_ld(&(bar)[XB_TMO])) break; if (_sp > XB_SPIN_CAP) { atomicAdd(&(bar)[XB_TMO], 1u); break; } } } } while (0)
; __device__ __forceinline__ void xcd_barrier(const XcdBarrier& b) {
;     ...
;             else XB_SPIN(xb_ld(&bar[XB_TOPGEN]) == tg, bar);
.LBB0_1364:
	global_load_dword v1, v0, s[8:9] offset:-256 sc1
	s_add_i32 s20, s20, 1
	s_mov_b64 s[18:19], -1
	s_waitcnt vmcnt(0)
	v_cmp_ge_u32_e32 vcc, v1, v2
	s_orn2_b64 s[34:35], vcc, exec
	s_branch .LBB0_1361

; __device__ __forceinline__ unsigned xb_add(unsigned* p, unsigned v) { return __hip_atomic_fetch_add(p, v, __ATOMIC_RELAXED, __HIP_MEMORY_SCOPE_AGENT); }
; __device__ __forceinline__ void xcd_barrier(const XcdBarrier& b) {
;     ...
;             __builtin_amdgcn_fence(__ATOMIC_ACQUIRE, "agent");
;             xb_add(&bar[XB_XGEN(b.x)], 1u);
;             asm volatile("s_waitcnt vmcnt(0)" ::: "memory");
.LBB0_1372:
	s_or_b64 exec, exec, s[6:7]
	s_mov_b64 s[6:7], exec
	v_mbcnt_lo_u32_b32 v0, s6, 0
	v_mbcnt_hi_u32_b32 v0, s7, v0
	v_cmp_eq_u32_e32 vcc, 0, v0
	s_waitcnt vmcnt(0)
	buffer_inv sc1
	s_and_saveexec_b64 s[8:9], vcc
	s_cbranch_execz .LBB0_1374
	s_bcnt1_i32_b64 s6, s[6:7]
	v_mov_b32_e32 v0, 0x2000
	v_mov_b32_e32 v1, s6
.LBB0_1374:
	s_or_b64 exec, exec, s[8:9]
	s_waitcnt vmcnt(0)
